# v30 with the attention QK priority raise held through row-max and the rescale decision (s_setprio 0 at the exp block)
# baseline (speedup 1.0000x reference)
; #define LAS __attribute__((address_space(3)))
; __device__ __forceinline__ void a2_qk(const LAS unsigned char* kb, const bf16x8 (&qf)[6], const f32x16& cneg, f32x16& st0, f32x16& st1) {
;     { const bf16x8 a0 = *(const LAS bf16x8*)(kb), a1 = *(const LAS bf16x8*)(kb + 32 * AT_KROW);
;       st0 = __builtin_amdgcn_mfma_f32_32x32x16_bf16(a0, qf[0], cneg, 0, 0, 0); st1 = __builtin_amdgcn_mfma_f32_32x32x16_bf16(a1, qf[0], cneg, 0, 0, 0); }
; #pragma unroll
;     for (int s = 1; s < 6; ++s) { const bf16x8 a0 = *(const LAS bf16x8*)(kb + s * 32), a1 = *(const LAS bf16x8*)(kb + 32 * AT_KROW + s * 32);
;         st0 = __builtin_amdgcn_mfma_f32_32x32x16_bf16(a0, qf[s], st0, 0, 0, 0); st1 = __builtin_amdgcn_mfma_f32_32x32x16_bf16(a1, qf[s], st1, 0, 0, 0); }
; }
; __device__ __forceinline__ void attn2_unit(bf16_t* Z, const bf16_t* Hb, const float* rc, const float* rs, LAS unsigned char* lds, int b, int h, int qblk) {
;     ...
;         if (2 * kp + 1 <= cw) {
;             f32x16 sa0, sa1, sb0, sb1; bf16x8 pa[4], pb[4];
;             __builtin_amdgcn_s_setprio(1);
;             a2_qk(kb, qf, cneg, sa0, sa1);
;             a2_qk(kb + 64 * AT_KROW, qf, cneg, sb0, sb1);
;             __builtin_amdgcn_s_setprio(0);
;             const float mt = fmaxf(a2_max(sa0, sa1), a2_max(sb0, sb1));
;             if (kp == 0 || __builtin_amdgcn_ballot_w64(mt > 8.f) != 0ull) {
;                 const float delta = (kp == 0) ? mt : fmaxf(mt, 0.f), alpha = (kp == 0) ? 0.f : __builtin_amdgcn_exp2f(-delta);
;                 mrun += delta; lsum *= alpha;
.LBB0_824:
	s_andn2_b64 vcc, exec, s[6:7]
	s_cbranch_vccnz .LBB0_833
	s_setprio 1
	v_add_u32_e32 v0, v3, v156
	ds_read_b128 v[4:7], v0
	ds_read_b128 v[8:11], v0 offset:6656
	ds_read_b128 v[12:15], v0 offset:32
	ds_read_b128 v[248:251], v0 offset:6688
	v_mov_b64_e32 v[94:95], v[62:63]
	v_mov_b64_e32 v[92:93], v[60:61]
	v_mov_b64_e32 v[90:91], v[58:59]
	v_mov_b64_e32 v[88:89], v[56:57]
	v_mov_b64_e32 v[86:87], v[54:55]
	v_mov_b64_e32 v[84:85], v[52:53]
	v_mov_b64_e32 v[82:83], v[50:51]
	v_mov_b64_e32 v[80:81], v[48:49]
	s_waitcnt lgkmcnt(3)
	v_mfma_f32_32x32x16_bf16 v[112:127], v[4:7], v[128:131], v[48:63]
	ds_read_b128 v[252:255], v0 offset:64
	s_waitcnt lgkmcnt(3)
	v_mfma_f32_32x32x16_bf16 v[96:111], v[8:11], v[128:131], v[48:63]
	ds_read_b128 v[4:7], v0 offset:6720
	s_waitcnt lgkmcnt(3)
	v_mfma_f32_32x32x16_bf16 v[112:127], v[12:15], v[132:135], v[112:127]
	ds_read_b128 v[8:11], v0 offset:96
	s_waitcnt lgkmcnt(3)
	v_mfma_f32_32x32x16_bf16 v[96:111], v[248:251], v[132:135], v[96:111]
	ds_read_b128 v[12:15], v0 offset:6752
	s_waitcnt lgkmcnt(3)
	v_mfma_f32_32x32x16_bf16 v[112:127], v[252:255], v[136:139], v[112:127]
	ds_read_b128 v[248:251], v0 offset:128
	s_waitcnt lgkmcnt(3)
	v_mfma_f32_32x32x16_bf16 v[96:111], v[4:7], v[136:139], v[96:111]
	ds_read_b128 v[252:255], v0 offset:6784
	s_waitcnt lgkmcnt(3)
	v_mfma_f32_32x32x16_bf16 v[112:127], v[8:11], v[140:143], v[112:127]
	ds_read_b128 v[4:7], v0 offset:160
	s_waitcnt lgkmcnt(3)
	v_mfma_f32_32x32x16_bf16 v[96:111], v[12:15], v[140:143], v[96:111]
	ds_read_b128 v[8:11], v0 offset:13312
	s_waitcnt lgkmcnt(3)
	v_mfma_f32_32x32x16_bf16 v[112:127], v[248:251], v[144:147], v[112:127]
	ds_read_b128 v[12:15], v0 offset:6816
	s_waitcnt lgkmcnt(3)
	v_mfma_f32_32x32x16_bf16 v[96:111], v[252:255], v[144:147], v[96:111]
	ds_read_b128 v[248:251], v0 offset:19968
	s_waitcnt lgkmcnt(3)
	v_mfma_f32_32x32x16_bf16 v[112:127], v[4:7], v[148:151], v[112:127]
	ds_read_b128 v[252:255], v0 offset:13344
	s_waitcnt lgkmcnt(3)
	v_mfma_f32_32x32x16_bf16 v[64:79], v[8:11], v[128:131], v[48:63]
	ds_read_b128 v[4:7], v0 offset:20000
	s_waitcnt lgkmcnt(3)
	v_mfma_f32_32x32x16_bf16 v[96:111], v[12:15], v[148:151], v[96:111]
	ds_read_b128 v[8:11], v0 offset:13376
	s_waitcnt lgkmcnt(3)
	v_mfma_f32_32x32x16_bf16 v[80:95], v[248:251], v[128:131], v[80:95]
	ds_read_b128 v[12:15], v0 offset:20032
	s_waitcnt lgkmcnt(3)
	v_mfma_f32_32x32x16_bf16 v[64:79], v[252:255], v[132:135], v[64:79]
	ds_read_b128 v[248:251], v0 offset:13408
	s_waitcnt lgkmcnt(3)
	v_mfma_f32_32x32x16_bf16 v[80:95], v[4:7], v[132:135], v[80:95]
	ds_read_b128 v[252:255], v0 offset:20064
	s_waitcnt lgkmcnt(3)
	v_mfma_f32_32x32x16_bf16 v[64:79], v[8:11], v[136:139], v[64:79]
	ds_read_b128 v[4:7], v0 offset:13440
	s_waitcnt lgkmcnt(3)
	v_mfma_f32_32x32x16_bf16 v[80:95], v[12:15], v[136:139], v[80:95]
	ds_read_b128 v[8:11], v0 offset:20096
	s_waitcnt lgkmcnt(3)
	v_mfma_f32_32x32x16_bf16 v[64:79], v[248:251], v[140:143], v[64:79]
	ds_read_b128 v[12:15], v0 offset:13472
	s_waitcnt lgkmcnt(3)
	v_mfma_f32_32x32x16_bf16 v[80:95], v[252:255], v[140:143], v[80:95]
	ds_read_b128 v[248:251], v0 offset:20128
	s_waitcnt lgkmcnt(3)
	v_mfma_f32_32x32x16_bf16 v[64:79], v[4:7], v[144:147], v[64:79]
	s_waitcnt lgkmcnt(2)
	v_mfma_f32_32x32x16_bf16 v[80:95], v[8:11], v[144:147], v[80:95]
	s_waitcnt lgkmcnt(1)
	v_mfma_f32_32x32x16_bf16 v[64:79], v[12:15], v[148:151], v[64:79]
	s_waitcnt lgkmcnt(0)
	v_mfma_f32_32x32x16_bf16 v[80:95], v[248:251], v[148:151], v[80:95]
	s_nop 0
	v_max_f32_e32 v0, v96, v96
	v_max_f32_e32 v3, v112, v112
	v_max_f32_e32 v0, v3, v0
	s_nop 7
	v_max_f32_e32 v3, v80, v80
	v_max_f32_e32 v4, v64, v64
	v_max_f32_e32 v3, v4, v3
	v_max3_f32 v3, v3, v65, v81
	v_max3_f32 v3, v3, v66, v82
	v_max3_f32 v0, v0, v113, v97
	v_max3_f32 v3, v3, v67, v83
	v_max3_f32 v0, v0, v114, v98
	v_max3_f32 v3, v3, v68, v84
	v_max3_f32 v0, v0, v115, v99
	v_max3_f32 v3, v3, v69, v85
	v_max3_f32 v0, v0, v116, v100
	v_max3_f32 v3, v3, v70, v86
	v_max3_f32 v0, v0, v117, v101
	v_max3_f32 v3, v3, v71, v87
	v_max3_f32 v0, v0, v118, v102
	v_max3_f32 v3, v3, v72, v88
	v_max3_f32 v0, v0, v119, v103
	v_max3_f32 v3, v3, v73, v89
	v_max3_f32 v0, v0, v120, v104
	v_max3_f32 v3, v3, v74, v90
	v_max3_f32 v0, v0, v121, v105
	v_max3_f32 v3, v3, v75, v91
	v_max3_f32 v0, v0, v122, v106
	v_max3_f32 v3, v3, v76, v92
	v_max3_f32 v0, v0, v123, v107
	v_max3_f32 v3, v3, v77, v93
	v_max3_f32 v0, v0, v124, v108
	v_max3_f32 v3, v3, v78, v94
	v_max3_f32 v3, v3, v79, v95
	v_max3_f32 v0, v0, v125, v109
	v_max3_f32 v0, v0, v126, v110
	v_max3_f32 v0, v0, v127, v111
	s_cmp_eq_u32 s65, 1
	v_max_f32_e32 v3, v3, v0
	v_mov_b32_e32 v4, v3
	v_mov_b32_e32 v5, v3
	s_cselect_b64 s[34:35], -1, 0
	s_cmp_lg_u32 s65, 1
	v_permlane32_swap_b32_e32 v4, v5
	v_max_f32_e32 v3, v4, v5
	s_cbranch_scc0 .LBB0_835
	v_cmp_lt_f32_e32 vcc, s53, v3
	s_mov_b64 s[24:25], 0
	s_mov_b64 s[6:7], 0
	s_cbranch_vccz .LBB0_828
	v_max_f32_e32 v0, v3, v3
	v_max_f32_e32 v0, 0, v0
	s_mov_b64 s[6:7], -1

; #define LAS __attribute__((address_space(3)))
; __device__ __forceinline__ void a2_exp_pack(f32x16& st0, f32x16& st1, float& lsum, bf16x8 (&pf)[4]) {
;     float ps = 0.f;
; #pragma unroll
;     for (int r = 0; r < 16; ++r) { st0[r] = __builtin_amdgcn_exp2f(st0[r]); st1[r] = __builtin_amdgcn_exp2f(st1[r]); ps += st0[r] + st1[r]; }
;     lsum += ps;
;     u32x4 w;
;     w.x = cvtpk2(st0[0], st0[1]); w.y = cvtpk2(st0[2], st0[3]); w.z = cvtpk2(st0[4], st0[5]); w.w = cvtpk2(st0[6], st0[7]); pf[0] = __builtin_bit_cast(bf16x8, w);
;     w.x = cvtpk2(st0[8], st0[9]); w.y = cvtpk2(st0[10], st0[11]); w.z = cvtpk2(st0[12], st0[13]); w.w = cvtpk2(st0[14], st0[15]); pf[1] = __builtin_bit_cast(bf16x8, w);
;     w.x = cvtpk2(st1[0], st1[1]); w.y = cvtpk2(st1[2], st1[3]); w.z = cvtpk2(st1[4], st1[5]); w.w = cvtpk2(st1[6], st1[7]); pf[2] = __builtin_bit_cast(bf16x8, w);
;     w.x = cvtpk2(st1[8], st1[9]); w.y = cvtpk2(st1[10], st1[11]); w.z = cvtpk2(st1[12], st1[13]); w.w = cvtpk2(st1[14], st1[15]); pf[3] = __builtin_bit_cast(bf16x8, w);
; }
; __device__ __forceinline__ void a2_pv(const LAS unsigned char* vb, const bf16x8 (&pf)[4], f32x16& ot0, f32x16& ot1) {
; #pragma unroll
;     for (int s = 0; s < 4; ++s) {
;         const s16x4 a00 = __builtin_bit_cast(s16x4, __builtin_amdgcn_ds_read_tr16_b64_v4i16((LAS s16x4*)(vb + (16 * s) * 64)));
;         const s16x4 a01 = __builtin_bit_cast(s16x4, __builtin_amdgcn_ds_read_tr16_b64_v4i16((LAS s16x4*)(vb + (16 * s + 8) * 64)));
;         const s16x4 a10 = __builtin_bit_cast(s16x4, __builtin_amdgcn_ds_read_tr16_b64_v4i16((LAS s16x4*)(vb + 8192 + (16 * s) * 64)));
;         const s16x4 a11 = __builtin_bit_cast(s16x4, __builtin_amdgcn_ds_read_tr16_b64_v4i16((LAS s16x4*)(vb + 8192 + (16 * s + 8) * 64)));
;         const bf16x8 va0 = (bf16x8){a00[0], a00[1], a00[2], a00[3], a01[0], a01[1], a01[2], a01[3]};
;         const bf16x8 va1 = (bf16x8){a10[0], a10[1], a10[2], a10[3], a11[0], a11[1], a11[2], a11[3]};
; __device__ __forceinline__ void attn2_unit(bf16_t* Z, const bf16_t* Hb, const float* rc, const float* rs, LAS unsigned char* lds, int b, int h, int qblk) {
;     ...
;             a2_exp_pack(sa0, sa1, lsum, pa);
;             a2_pv(vb, pa, ot0, ot1);
;             a2_exp_pack(sb0, sb1, lsum, pb);
;             a2_pv(vb + 64 * 64, pb, ot0, ot1);
.LBB0_832:
	s_setprio 0
	v_add_u32_e32 v0, v2, v218
	v_exp_f32_e32 v199, v112
	v_exp_f32_e32 v7, v96
	v_exp_f32_e32 v113, v113
	v_exp_f32_e32 v9, v97
	v_exp_f32_e32 v201, v114
	v_exp_f32_e32 v3, v98
	v_exp_f32_e32 v115, v115
	v_exp_f32_e32 v5, v99
	v_exp_f32_e32 v203, v116
	v_exp_f32_e32 v15, v117
	v_exp_f32_e32 v13, v118
	v_exp_f32_e32 v11, v119
	s_waitcnt vmcnt(0)
	ds_read_b64_tr_b16 v[96:97], v0 offset:26624
	ds_read_b64_tr_b16 v[98:99], v0 offset:27136
	ds_read_b64_tr_b16 v[214:215], v0 offset:34816
	ds_read_b64_tr_b16 v[216:217], v0 offset:35328
	ds_read_b64_tr_b16 v[224:225], v0 offset:27648
	ds_read_b64_tr_b16 v[226:227], v0 offset:28160
	v_cvt_pk_bf16_f32 v210, v199, v113
	v_cvt_pk_bf16_f32 v211, v201, v115
	v_cvt_pk_bf16_f32 v212, v203, v15
	v_cvt_pk_bf16_f32 v213, v13, v11
	v_exp_f32_e32 v209, v120
	v_exp_f32_e32 v207, v121
	s_waitcnt lgkmcnt(4)
	v_mfma_f32_32x32x16_bf16 v[16:31], v[96:99], v[210:213], v[16:31]
	v_exp_f32_e32 v205, v122
	v_exp_f32_e32 v121, v123
	v_exp_f32_e32 v117, v124
	ds_read_b64_tr_b16 v[228:229], v0 offset:35840
	ds_read_b64_tr_b16 v[230:231], v0 offset:36352
	v_exp_f32_e32 v119, v125
	v_exp_f32_e32 v99, v126
	v_exp_f32_e32 v97, v127
	s_waitcnt lgkmcnt(4)
	v_mfma_f32_32x32x16_bf16 v[32:47], v[214:217], v[210:213], v[32:47]
	v_cvt_pk_bf16_f32 v232, v209, v207
	v_cvt_pk_bf16_f32 v233, v205, v121
	v_cvt_pk_bf16_f32 v234, v117, v119
	v_cvt_pk_bf16_f32 v235, v99, v97
	v_exp_f32_e32 v125, v100
	v_exp_f32_e32 v213, v101
	v_exp_f32_e32 v211, v102
	s_waitcnt lgkmcnt(2)
	v_mfma_f32_32x32x16_bf16 v[16:31], v[224:227], v[232:235], v[16:31]
	v_exp_f32_e32 v217, v103
	ds_read_b64_tr_b16 v[224:225], v0 offset:28672
	ds_read_b64_tr_b16 v[226:227], v0 offset:29184
	v_cvt_pk_bf16_f32 v100, v7, v9
	v_cvt_pk_bf16_f32 v101, v3, v5
	v_cvt_pk_bf16_f32 v102, v125, v213
	v_cvt_pk_bf16_f32 v103, v211, v217
	v_exp_f32_e32 v123, v104
	s_waitcnt lgkmcnt(2)
	v_mfma_f32_32x32x16_bf16 v[32:47], v[228:231], v[232:235], v[32:47]
	ds_read_b64_tr_b16 v[228:229], v0 offset:36864
	ds_read_b64_tr_b16 v[230:231], v0 offset:37376
	ds_read_b64_tr_b16 v[232:233], v0 offset:29696
	ds_read_b64_tr_b16 v[234:235], v0 offset:30208
	v_exp_f32_e32 v127, v105
	v_exp_f32_e32 v105, v106
	v_exp_f32_e32 v215, v107
	v_exp_f32_e32 v107, v108
	v_exp_f32_e32 v109, v109
	v_exp_f32_e32 v198, v64
	s_waitcnt lgkmcnt(4)
	v_mfma_f32_32x32x16_bf16 v[16:31], v[224:227], v[100:103], v[16:31]
	ds_read_b64_tr_b16 v[224:225], v0 offset:37888
	ds_read_b64_tr_b16 v[226:227], v0 offset:38400
	v_exp_f32_e32 v6, v80
	v_exp_f32_e32 v112, v65
	v_exp_f32_e32 v8, v81
	v_exp_f32_e32 v200, v66
	v_exp_f32_e32 v2, v82
	v_exp_f32_e32 v114, v67
	s_waitcnt lgkmcnt(4)
	v_mfma_f32_32x32x16_bf16 v[32:47], v[228:231], v[100:103], v[32:47]
	v_exp_f32_e32 v103, v110
	v_exp_f32_e32 v101, v111
	v_exp_f32_e32 v4, v83
	v_cvt_pk_bf16_f32 v228, v123, v127
	v_cvt_pk_bf16_f32 v229, v105, v215
	v_cvt_pk_bf16_f32 v230, v107, v109
	v_cvt_pk_bf16_f32 v231, v103, v101
	v_pk_add_f32 v[64:65], v[6:7], v[198:199]
	v_pk_add_f32 v[66:67], v[8:9], v[112:113]
	s_waitcnt lgkmcnt(2)
	v_mfma_f32_32x32x16_bf16 v[16:31], v[232:235], v[228:231], v[16:31]
	v_add_f32_e64 v64, v64, 0
	v_add_f32_e64 v65, v65, 0
	v_exp_f32_e32 v202, v68
	v_pk_add_f32 v[64:65], v[66:67], v[64:65]
	v_pk_add_f32 v[66:67], v[2:3], v[200:201]
	v_exp_f32_e32 v14, v69
	v_pk_add_f32 v[64:65], v[66:67], v[64:65]
	v_pk_add_f32 v[66:67], v[4:5], v[114:115]
	s_waitcnt lgkmcnt(0)
	v_mfma_f32_32x32x16_bf16 v[32:47], v[224:227], v[228:231], v[32:47]
	v_add_f32_e64 v110, v66, v64
	v_add_f32_e64 v111, v67, v65
	v_exp_f32_e32 v12, v70
	v_exp_f32_e32 v10, v71
	ds_read_b64_tr_b16 v[64:65], v0 offset:30720
	ds_read_b64_tr_b16 v[66:67], v0 offset:31232
	v_exp_f32_e32 v124, v84
	v_exp_f32_e32 v208, v72
	v_exp_f32_e32 v206, v73
	v_exp_f32_e32 v204, v74
	v_exp_f32_e32 v120, v75
	ds_read_b64_tr_b16 v[72:73], v0 offset:38912
	ds_read_b64_tr_b16 v[74:75], v0 offset:39424
	ds_read_b64_tr_b16 v[80:81], v0 offset:31744
	ds_read_b64_tr_b16 v[82:83], v0 offset:32256
	v_exp_f32_e32 v212, v85
	v_cvt_pk_bf16_f32 v68, v198, v112
	v_cvt_pk_bf16_f32 v69, v200, v114
	v_cvt_pk_bf16_f32 v70, v202, v14
	v_cvt_pk_bf16_f32 v71, v12, v10
	v_pk_add_f32 v[220:221], v[124:125], v[202:203]
	v_exp_f32_e32 v210, v86
	s_waitcnt lgkmcnt(4)
; __device__ __forceinline__ void attn2_unit(bf16_t* Z, const bf16_t* Hb, const float* rc, const float* rs, LAS unsigned char* lds, int b, int h, int qblk) {
;     ...
;             a2_exp_pack(sa0, sa1, lsum, pa);
;             a2_pv(vb, pa, ot0, ot1);
;             a2_exp_pack(sb0, sb1, lsum, pb);
;             a2_pv(vb + 64 * 64, pb, ot0, ot1);
;         } else if (2 * kp <= cw) {
;             f32x16 sa0, sa1; bf16x8 pa[4];
;             a2_qk(kb, qf, cneg, sa0, sa1);
;             const float mt = a2_max(sa0, sa1);
;             if (kp == 0 || __builtin_amdgcn_ballot_w64(mt > 8.f) != 0ull) {
;                 const float delta = (kp == 0) ? mt : fmaxf(mt, 0.f), alpha = (kp == 0) ? 0.f : __builtin_amdgcn_exp2f(-delta);
;                 mrun += delta; lsum *= alpha;
; #pragma unroll
;                 for (int r = 0; r < 16; ++r) { ot0[r] *= alpha; ot1[r] *= alpha; sa0[r] -= delta; sa1[r] -= delta; cneg[r] = -mrun; }
;             }
;             a2_exp_pack(sa0, sa1, lsum, pa);
;             a2_pv(vb, pa, ot0, ot1);
;         }
;         __syncthreads();
;     }
	v_mfma_f32_32x32x16_bf16 v[16:31], v[64:67], v[68:71], v[16:31]
	v_add_f32_e64 v64, v220, v110
	v_add_f32_e64 v65, v221, v111
	v_add_f32_e64 v14, v212, v14
	v_add_f32_e64 v15, v213, v15
	v_exp_f32_e32 v216, v87
	v_exp_f32_e32 v116, v76
	v_exp_f32_e32 v118, v77
	v_exp_f32_e32 v98, v78
	v_exp_f32_e32 v96, v79
	s_waitcnt lgkmcnt(2)
	v_mfma_f32_32x32x16_bf16 v[32:47], v[72:75], v[68:71], v[32:47]
	v_add_f32_e64 v14, v14, v64
	v_add_f32_e64 v15, v15, v65
	ds_read_b64_tr_b16 v[64:65], v0 offset:39936
	ds_read_b64_tr_b16 v[66:67], v0 offset:40448
	v_exp_f32_e32 v122, v88
	v_pk_add_f32 v[12:13], v[210:211], v[12:13]
	v_pk_add_f32 v[68:69], v[216:217], v[10:11]
	v_pk_add_f32 v[14:15], v[12:13], v[14:15]
	v_cvt_pk_bf16_f32 v10, v208, v206
	v_cvt_pk_bf16_f32 v11, v204, v120
	v_cvt_pk_bf16_f32 v12, v116, v118
	v_cvt_pk_bf16_f32 v13, v98, v96
	v_pk_add_f32 v[14:15], v[68:69], v[14:15]
	v_pk_add_f32 v[68:69], v[122:123], v[208:209]
	s_waitcnt lgkmcnt(2)
	v_mfma_f32_32x32x16_bf16 v[16:31], v[80:83], v[10:13], v[16:31]
	v_add_f32_e64 v14, v68, v14
	v_add_f32_e64 v15, v69, v15
	ds_read_b64_tr_b16 v[68:69], v0 offset:32768
	ds_read_b64_tr_b16 v[70:71], v0 offset:33280
	v_exp_f32_e32 v126, v89
	v_exp_f32_e32 v104, v90
	v_cvt_pk_bf16_f32 v7, v2, v4
	v_exp_f32_e32 v214, v91
	v_cvt_pk_bf16_f32 v6, v6, v8
	s_waitcnt lgkmcnt(2)
	v_mfma_f32_32x32x16_bf16 v[32:47], v[64:67], v[10:13], v[32:47]
	ds_read_b64_tr_b16 v[2:3], v0 offset:40960
	ds_read_b64_tr_b16 v[4:5], v0 offset:41472
	ds_read_b64_tr_b16 v[10:11], v0 offset:33792
	ds_read_b64_tr_b16 v[12:13], v0 offset:34304
	v_cvt_pk_bf16_f32 v8, v124, v212
	v_cvt_pk_bf16_f32 v9, v210, v216
	v_pk_add_f32 v[72:73], v[126:127], v[206:207]
	v_pk_add_f32 v[64:65], v[104:105], v[204:205]
	v_pk_add_f32 v[14:15], v[72:73], v[14:15]
	v_exp_f32_e32 v106, v92
	s_waitcnt lgkmcnt(4)
	v_mfma_f32_32x32x16_bf16 v[16:31], v[68:71], v[6:9], v[16:31]
	v_add_f32_e64 v14, v64, v14
	v_add_f32_e64 v15, v65, v15
	v_add_f32_e64 v64, v214, v120
	v_add_f32_e64 v65, v215, v121
	v_exp_f32_e32 v108, v93
	v_exp_f32_e32 v102, v94
	v_exp_f32_e32 v100, v95
	v_pk_add_f32 v[14:15], v[64:65], v[14:15]
	ds_read_b64_tr_b16 v[64:65], v0 offset:41984
	ds_read_b64_tr_b16 v[66:67], v0 offset:42496
	s_waitcnt lgkmcnt(4)
	v_mfma_f32_32x32x16_bf16 v[32:47], v[2:5], v[6:9], v[32:47]
	v_add_f32_e64 v2, v106, v116
	v_add_f32_e64 v3, v107, v117
	v_cvt_pk_bf16_f32 v4, v106, v108
	v_add_f32_e64 v6, v2, v14
	v_add_f32_e64 v7, v3, v15
	v_cvt_pk_bf16_f32 v2, v122, v126
	v_cvt_pk_bf16_f32 v3, v104, v214
	v_cvt_pk_bf16_f32 v5, v102, v100
	v_pk_add_f32 v[8:9], v[108:109], v[118:119]
	v_mov_b32_e32 v14, v55
	s_waitcnt lgkmcnt(2)
	v_mfma_f32_32x32x16_bf16 v[16:31], v[10:13], v[2:5], v[16:31]
	v_add_f32_e64 v6, v8, v6
	v_add_f32_e64 v7, v9, v7
	v_add_f32_e64 v8, v102, v98
	v_add_f32_e64 v9, v103, v99
	v_mov_b32_e32 v10, v59
	v_pk_add_f32 v[6:7], v[8:9], v[6:7]
	v_pk_add_f32 v[8:9], v[100:101], v[96:97]
	v_mov_b32_e32 v11, v58
	v_pk_add_f32 v[6:7], v[8:9], v[6:7]
	s_waitcnt lgkmcnt(0)
	v_mfma_f32_32x32x16_bf16 v[32:47], v[64:67], v[2:5], v[32:47]
	v_add_f32_e32 v0, v169, v7
	v_add_f32_e32 v0, v6, v0
	s_add_i32 s65, s65, 1
	s_add_i32 s69, s69, 2
	s_add_i32 s6, s43, s65
	v_lshl_add_u64 v[176:177], v[176:177], 0, v[174:175]
	v_lshl_add_u64 v[178:179], v[178:179], 0, s[20:21]
	v_lshl_add_u64 v[180:181], v[180:181], 0, s[20:21]
	v_lshl_add_u64 v[184:185], v[184:185], 0, v[182:183]
	v_lshl_add_u64 v[188:189], v[188:189], 0, v[186:187]
	s_cmp_lg_u32 s6, 1
	v_lshl_add_u64 v[196:197], v[196:197], 0, v[190:191]
	s_waitcnt vmcnt(0) lgkmcnt(0)
	s_barrier
	s_cbranch_scc0 .Lattn_exit_0
	v_mov_b32_e32 v169, v0
	s_bitcmp1_b32 s65, 0
	s_cselect_b32 s6, 0, 0xa800
	s_cmp_ge_u32 s65, s36
	s_cbranch_scc0 .LBB0_810
	s_branch .LBB0_813

; #define LAS __attribute__((address_space(3)))
; __device__ __forceinline__ void a2_qk(const LAS unsigned char* kb, const bf16x8 (&qf)[6], const f32x16& cneg, f32x16& st0, f32x16& st1) {
;     { const bf16x8 a0 = *(const LAS bf16x8*)(kb), a1 = *(const LAS bf16x8*)(kb + 32 * AT_KROW);
;       st0 = __builtin_amdgcn_mfma_f32_32x32x16_bf16(a0, qf[0], cneg, 0, 0, 0); st1 = __builtin_amdgcn_mfma_f32_32x32x16_bf16(a1, qf[0], cneg, 0, 0, 0); }
; #pragma unroll
;     for (int s = 1; s < 6; ++s) { const bf16x8 a0 = *(const LAS bf16x8*)(kb + s * 32), a1 = *(const LAS bf16x8*)(kb + 32 * AT_KROW + s * 32);
;         st0 = __builtin_amdgcn_mfma_f32_32x32x16_bf16(a0, qf[s], st0, 0, 0, 0); st1 = __builtin_amdgcn_mfma_f32_32x32x16_bf16(a1, qf[s], st1, 0, 0, 0); }
; }
; __device__ __forceinline__ void attn2_unit(bf16_t* Z, const bf16_t* Hb, const float* rc, const float* rs, LAS unsigned char* lds, int b, int h, int qblk) {
;     ...
;         if (2 * kp + 1 <= cw) {
;             f32x16 sa0, sa1, sb0, sb1; bf16x8 pa[4], pb[4];
;             __builtin_amdgcn_s_setprio(1);
;             a2_qk(kb, qf, cneg, sa0, sa1);
;             a2_qk(kb + 64 * AT_KROW, qf, cneg, sb0, sb1);
;             __builtin_amdgcn_s_setprio(0);
;             const float mt = fmaxf(a2_max(sa0, sa1), a2_max(sb0, sb1));
;             if (kp == 0 || __builtin_amdgcn_ballot_w64(mt > 8.f) != 0ull) {
;                 const float delta = (kp == 0) ? mt : fmaxf(mt, 0.f), alpha = (kp == 0) ? 0.f : __builtin_amdgcn_exp2f(-delta);
;                 mrun += delta; lsum *= alpha;
.LBB0_870:
	s_andn2_b64 vcc, exec, s[6:7]
	s_cbranch_vccnz .LBB0_879
	s_setprio 1
	v_add_u32_e32 v0, v3, v156
	ds_read_b128 v[4:7], v0
	ds_read_b128 v[8:11], v0 offset:6656
	ds_read_b128 v[12:15], v0 offset:32
	ds_read_b128 v[248:251], v0 offset:6688
	v_mov_b64_e32 v[94:95], v[62:63]
	v_mov_b64_e32 v[92:93], v[60:61]
	v_mov_b64_e32 v[90:91], v[58:59]
	v_mov_b64_e32 v[88:89], v[56:57]
	v_mov_b64_e32 v[86:87], v[54:55]
	v_mov_b64_e32 v[84:85], v[52:53]
	v_mov_b64_e32 v[82:83], v[50:51]
	v_mov_b64_e32 v[80:81], v[48:49]
	s_waitcnt lgkmcnt(3)
	v_mfma_f32_32x32x16_bf16 v[112:127], v[4:7], v[128:131], v[48:63]
	ds_read_b128 v[252:255], v0 offset:64
	s_waitcnt lgkmcnt(3)
	v_mfma_f32_32x32x16_bf16 v[96:111], v[8:11], v[128:131], v[48:63]
	ds_read_b128 v[4:7], v0 offset:6720
	s_waitcnt lgkmcnt(3)
	v_mfma_f32_32x32x16_bf16 v[112:127], v[12:15], v[132:135], v[112:127]
	ds_read_b128 v[8:11], v0 offset:96
	s_waitcnt lgkmcnt(3)
	v_mfma_f32_32x32x16_bf16 v[96:111], v[248:251], v[132:135], v[96:111]
	ds_read_b128 v[12:15], v0 offset:6752
	s_waitcnt lgkmcnt(3)
	v_mfma_f32_32x32x16_bf16 v[112:127], v[252:255], v[136:139], v[112:127]
	ds_read_b128 v[248:251], v0 offset:128
	s_waitcnt lgkmcnt(3)
	v_mfma_f32_32x32x16_bf16 v[96:111], v[4:7], v[136:139], v[96:111]
	ds_read_b128 v[252:255], v0 offset:6784
	s_waitcnt lgkmcnt(3)
	v_mfma_f32_32x32x16_bf16 v[112:127], v[8:11], v[140:143], v[112:127]
	ds_read_b128 v[4:7], v0 offset:160
	s_waitcnt lgkmcnt(3)
	v_mfma_f32_32x32x16_bf16 v[96:111], v[12:15], v[140:143], v[96:111]
	ds_read_b128 v[8:11], v0 offset:13312
	s_waitcnt lgkmcnt(3)
	v_mfma_f32_32x32x16_bf16 v[112:127], v[248:251], v[144:147], v[112:127]
	ds_read_b128 v[12:15], v0 offset:6816
	s_waitcnt lgkmcnt(3)
	v_mfma_f32_32x32x16_bf16 v[96:111], v[252:255], v[144:147], v[96:111]
	ds_read_b128 v[248:251], v0 offset:19968
	s_waitcnt lgkmcnt(3)
	v_mfma_f32_32x32x16_bf16 v[112:127], v[4:7], v[148:151], v[112:127]
	ds_read_b128 v[252:255], v0 offset:13344
	s_waitcnt lgkmcnt(3)
	v_mfma_f32_32x32x16_bf16 v[64:79], v[8:11], v[128:131], v[48:63]
	ds_read_b128 v[4:7], v0 offset:20000
	s_waitcnt lgkmcnt(3)
	v_mfma_f32_32x32x16_bf16 v[96:111], v[12:15], v[148:151], v[96:111]
	ds_read_b128 v[8:11], v0 offset:13376
	s_waitcnt lgkmcnt(3)
	v_mfma_f32_32x32x16_bf16 v[80:95], v[248:251], v[128:131], v[80:95]
	ds_read_b128 v[12:15], v0 offset:20032
	s_waitcnt lgkmcnt(3)
	v_mfma_f32_32x32x16_bf16 v[64:79], v[252:255], v[132:135], v[64:79]
	ds_read_b128 v[248:251], v0 offset:13408
	s_waitcnt lgkmcnt(3)
	v_mfma_f32_32x32x16_bf16 v[80:95], v[4:7], v[132:135], v[80:95]
	ds_read_b128 v[252:255], v0 offset:20064
	s_waitcnt lgkmcnt(3)
	v_mfma_f32_32x32x16_bf16 v[64:79], v[8:11], v[136:139], v[64:79]
	ds_read_b128 v[4:7], v0 offset:13440
	s_waitcnt lgkmcnt(3)
	v_mfma_f32_32x32x16_bf16 v[80:95], v[12:15], v[136:139], v[80:95]
	ds_read_b128 v[8:11], v0 offset:20096
	s_waitcnt lgkmcnt(3)
	v_mfma_f32_32x32x16_bf16 v[64:79], v[248:251], v[140:143], v[64:79]
	ds_read_b128 v[12:15], v0 offset:13472
	s_waitcnt lgkmcnt(3)
	v_mfma_f32_32x32x16_bf16 v[80:95], v[252:255], v[140:143], v[80:95]
	ds_read_b128 v[248:251], v0 offset:20128
	s_waitcnt lgkmcnt(3)
	v_mfma_f32_32x32x16_bf16 v[64:79], v[4:7], v[144:147], v[64:79]
	s_waitcnt lgkmcnt(2)
	v_mfma_f32_32x32x16_bf16 v[80:95], v[8:11], v[144:147], v[80:95]
	s_waitcnt lgkmcnt(1)
	v_mfma_f32_32x32x16_bf16 v[64:79], v[12:15], v[148:151], v[64:79]
	s_waitcnt lgkmcnt(0)
	v_mfma_f32_32x32x16_bf16 v[80:95], v[248:251], v[148:151], v[80:95]
	s_nop 0
	v_max_f32_e32 v0, v96, v96
	v_max_f32_e32 v3, v112, v112
	v_max_f32_e32 v0, v3, v0
	s_nop 7
	v_max_f32_e32 v3, v80, v80
	v_max_f32_e32 v4, v64, v64
	v_max_f32_e32 v3, v4, v3
	v_max3_f32 v3, v3, v65, v81
	v_max3_f32 v3, v3, v66, v82
	v_max3_f32 v0, v0, v113, v97
	v_max3_f32 v3, v3, v67, v83
	v_max3_f32 v0, v0, v114, v98
	v_max3_f32 v3, v3, v68, v84
	v_max3_f32 v0, v0, v115, v99
	v_max3_f32 v3, v3, v69, v85
	v_max3_f32 v0, v0, v116, v100
	v_max3_f32 v3, v3, v70, v86
	v_max3_f32 v0, v0, v117, v101
	v_max3_f32 v3, v3, v71, v87
	v_max3_f32 v0, v0, v118, v102
	v_max3_f32 v3, v3, v72, v88
	v_max3_f32 v0, v0, v119, v103
	v_max3_f32 v3, v3, v73, v89
	v_max3_f32 v0, v0, v120, v104
	v_max3_f32 v3, v3, v74, v90
	v_max3_f32 v0, v0, v121, v105
	v_max3_f32 v3, v3, v75, v91
	v_max3_f32 v0, v0, v122, v106
	v_max3_f32 v3, v3, v76, v92
	v_max3_f32 v0, v0, v123, v107
	v_max3_f32 v3, v3, v77, v93
	v_max3_f32 v0, v0, v124, v108
	v_max3_f32 v3, v3, v78, v94
	v_max3_f32 v3, v3, v79, v95
	v_max3_f32 v0, v0, v125, v109
	v_max3_f32 v0, v0, v126, v110
	v_max3_f32 v0, v0, v127, v111
	s_cmp_eq_u32 s35, 1
	v_max_f32_e32 v3, v3, v0
	v_mov_b32_e32 v4, v3
	v_mov_b32_e32 v5, v3
	s_cselect_b64 s[28:29], -1, 0
	s_cmp_lg_u32 s35, 1
	v_permlane32_swap_b32_e32 v4, v5
	v_max_f32_e32 v3, v4, v5
	s_cbranch_scc0 .LBB0_881
	v_cmp_lt_f32_e32 vcc, s53, v3
	s_mov_b64 s[24:25], 0
	s_mov_b64 s[6:7], 0
	s_cbranch_vccz .LBB0_874
	v_max_f32_e32 v0, v3, v3
	v_max_f32_e32 v0, 0, v0
	s_mov_b64 s[6:7], -1

; #define LAS __attribute__((address_space(3)))
; __device__ __forceinline__ void a2_exp_pack(f32x16& st0, f32x16& st1, float& lsum, bf16x8 (&pf)[4]) {
;     float ps = 0.f;
; #pragma unroll
;     for (int r = 0; r < 16; ++r) { st0[r] = __builtin_amdgcn_exp2f(st0[r]); st1[r] = __builtin_amdgcn_exp2f(st1[r]); ps += st0[r] + st1[r]; }
;     lsum += ps;
;     u32x4 w;
;     w.x = cvtpk2(st0[0], st0[1]); w.y = cvtpk2(st0[2], st0[3]); w.z = cvtpk2(st0[4], st0[5]); w.w = cvtpk2(st0[6], st0[7]); pf[0] = __builtin_bit_cast(bf16x8, w);
;     w.x = cvtpk2(st0[8], st0[9]); w.y = cvtpk2(st0[10], st0[11]); w.z = cvtpk2(st0[12], st0[13]); w.w = cvtpk2(st0[14], st0[15]); pf[1] = __builtin_bit_cast(bf16x8, w);
;     w.x = cvtpk2(st1[0], st1[1]); w.y = cvtpk2(st1[2], st1[3]); w.z = cvtpk2(st1[4], st1[5]); w.w = cvtpk2(st1[6], st1[7]); pf[2] = __builtin_bit_cast(bf16x8, w);
;     w.x = cvtpk2(st1[8], st1[9]); w.y = cvtpk2(st1[10], st1[11]); w.z = cvtpk2(st1[12], st1[13]); w.w = cvtpk2(st1[14], st1[15]); pf[3] = __builtin_bit_cast(bf16x8, w);
; }
; __device__ __forceinline__ void a2_pv(const LAS unsigned char* vb, const bf16x8 (&pf)[4], f32x16& ot0, f32x16& ot1) {
; #pragma unroll
;     for (int s = 0; s < 4; ++s) {
;         const s16x4 a00 = __builtin_bit_cast(s16x4, __builtin_amdgcn_ds_read_tr16_b64_v4i16((LAS s16x4*)(vb + (16 * s) * 64)));
;         const s16x4 a01 = __builtin_bit_cast(s16x4, __builtin_amdgcn_ds_read_tr16_b64_v4i16((LAS s16x4*)(vb + (16 * s + 8) * 64)));
;         const s16x4 a10 = __builtin_bit_cast(s16x4, __builtin_amdgcn_ds_read_tr16_b64_v4i16((LAS s16x4*)(vb + 8192 + (16 * s) * 64)));
;         const s16x4 a11 = __builtin_bit_cast(s16x4, __builtin_amdgcn_ds_read_tr16_b64_v4i16((LAS s16x4*)(vb + 8192 + (16 * s + 8) * 64)));
;         const bf16x8 va0 = (bf16x8){a00[0], a00[1], a00[2], a00[3], a01[0], a01[1], a01[2], a01[3]};
;         const bf16x8 va1 = (bf16x8){a10[0], a10[1], a10[2], a10[3], a11[0], a11[1], a11[2], a11[3]};
; __device__ __forceinline__ void attn2_unit(bf16_t* Z, const bf16_t* Hb, const float* rc, const float* rs, LAS unsigned char* lds, int b, int h, int qblk) {
;     ...
;             a2_exp_pack(sa0, sa1, lsum, pa);
;             a2_pv(vb, pa, ot0, ot1);
;             a2_exp_pack(sb0, sb1, lsum, pb);
;             a2_pv(vb + 64 * 64, pb, ot0, ot1);
.LBB0_878:
	s_setprio 0
	v_add_u32_e32 v0, v2, v218
	v_exp_f32_e32 v197, v112
	v_exp_f32_e32 v7, v96
	v_exp_f32_e32 v113, v113
	v_exp_f32_e32 v9, v97
	v_exp_f32_e32 v199, v114
	v_exp_f32_e32 v3, v98
	v_exp_f32_e32 v115, v115
	v_exp_f32_e32 v5, v99
	v_exp_f32_e32 v201, v116
	v_exp_f32_e32 v15, v117
	v_exp_f32_e32 v13, v118
	v_exp_f32_e32 v11, v119
	s_waitcnt vmcnt(0)
	ds_read_b64_tr_b16 v[96:97], v0 offset:26624
	ds_read_b64_tr_b16 v[98:99], v0 offset:27136
	ds_read_b64_tr_b16 v[212:213], v0 offset:34816
	ds_read_b64_tr_b16 v[214:215], v0 offset:35328
	ds_read_b64_tr_b16 v[224:225], v0 offset:27648
	ds_read_b64_tr_b16 v[226:227], v0 offset:28160
	v_cvt_pk_bf16_f32 v208, v197, v113
	v_cvt_pk_bf16_f32 v209, v199, v115
	v_cvt_pk_bf16_f32 v210, v201, v15
	v_cvt_pk_bf16_f32 v211, v13, v11
	v_exp_f32_e32 v207, v120
	v_exp_f32_e32 v205, v121
	s_waitcnt lgkmcnt(4)
	v_mfma_f32_32x32x16_bf16 v[16:31], v[96:99], v[208:211], v[16:31]
	v_exp_f32_e32 v203, v122
	v_exp_f32_e32 v121, v123
	v_exp_f32_e32 v117, v124
	ds_read_b64_tr_b16 v[228:229], v0 offset:35840
	ds_read_b64_tr_b16 v[230:231], v0 offset:36352
	v_exp_f32_e32 v119, v125
	v_exp_f32_e32 v99, v126
	v_exp_f32_e32 v97, v127
	s_waitcnt lgkmcnt(4)
	v_mfma_f32_32x32x16_bf16 v[32:47], v[212:215], v[208:211], v[32:47]
	v_cvt_pk_bf16_f32 v232, v207, v205
	v_cvt_pk_bf16_f32 v233, v203, v121
	v_cvt_pk_bf16_f32 v234, v117, v119
	v_cvt_pk_bf16_f32 v235, v99, v97
	v_exp_f32_e32 v125, v100
	v_exp_f32_e32 v211, v101
	v_exp_f32_e32 v209, v102
	s_waitcnt lgkmcnt(2)
	v_mfma_f32_32x32x16_bf16 v[16:31], v[224:227], v[232:235], v[16:31]
	v_exp_f32_e32 v215, v103
	ds_read_b64_tr_b16 v[224:225], v0 offset:28672
	ds_read_b64_tr_b16 v[226:227], v0 offset:29184
	v_cvt_pk_bf16_f32 v100, v7, v9
	v_cvt_pk_bf16_f32 v101, v3, v5
	v_cvt_pk_bf16_f32 v102, v125, v211
	v_cvt_pk_bf16_f32 v103, v209, v215
	v_exp_f32_e32 v123, v104
	s_waitcnt lgkmcnt(2)
	v_mfma_f32_32x32x16_bf16 v[32:47], v[228:231], v[232:235], v[32:47]
	ds_read_b64_tr_b16 v[228:229], v0 offset:36864
	ds_read_b64_tr_b16 v[230:231], v0 offset:37376
	ds_read_b64_tr_b16 v[232:233], v0 offset:29696
	ds_read_b64_tr_b16 v[234:235], v0 offset:30208
	v_exp_f32_e32 v127, v105
	v_exp_f32_e32 v105, v106
	v_exp_f32_e32 v213, v107
	v_exp_f32_e32 v107, v108
	v_exp_f32_e32 v109, v109
	v_exp_f32_e32 v196, v64
	s_waitcnt lgkmcnt(4)
	v_mfma_f32_32x32x16_bf16 v[16:31], v[224:227], v[100:103], v[16:31]
	ds_read_b64_tr_b16 v[224:225], v0 offset:37888
	ds_read_b64_tr_b16 v[226:227], v0 offset:38400
	v_exp_f32_e32 v6, v80
	v_exp_f32_e32 v112, v65
	v_exp_f32_e32 v8, v81
	v_exp_f32_e32 v198, v66
	v_exp_f32_e32 v2, v82
	v_exp_f32_e32 v114, v67
	s_waitcnt lgkmcnt(4)
	v_mfma_f32_32x32x16_bf16 v[32:47], v[228:231], v[100:103], v[32:47]
	v_exp_f32_e32 v103, v110
	v_exp_f32_e32 v101, v111
	v_exp_f32_e32 v4, v83
	v_cvt_pk_bf16_f32 v228, v123, v127
	v_cvt_pk_bf16_f32 v229, v105, v213
	v_cvt_pk_bf16_f32 v230, v107, v109
	v_cvt_pk_bf16_f32 v231, v103, v101
	v_pk_add_f32 v[64:65], v[6:7], v[196:197]
	v_pk_add_f32 v[66:67], v[8:9], v[112:113]
	s_waitcnt lgkmcnt(2)
	v_mfma_f32_32x32x16_bf16 v[16:31], v[232:235], v[228:231], v[16:31]
	v_add_f32_e64 v64, v64, 0
	v_add_f32_e64 v65, v65, 0
	v_exp_f32_e32 v200, v68
	v_pk_add_f32 v[64:65], v[66:67], v[64:65]
	v_pk_add_f32 v[66:67], v[2:3], v[198:199]
	v_exp_f32_e32 v14, v69
	v_pk_add_f32 v[64:65], v[66:67], v[64:65]
	v_pk_add_f32 v[66:67], v[4:5], v[114:115]
	s_waitcnt lgkmcnt(0)
	v_mfma_f32_32x32x16_bf16 v[32:47], v[224:227], v[228:231], v[32:47]
	v_add_f32_e64 v110, v66, v64
	v_add_f32_e64 v111, v67, v65
	v_exp_f32_e32 v12, v70
	v_exp_f32_e32 v10, v71
	ds_read_b64_tr_b16 v[64:65], v0 offset:30720
	ds_read_b64_tr_b16 v[66:67], v0 offset:31232
	v_exp_f32_e32 v124, v84
	v_exp_f32_e32 v206, v72
	v_exp_f32_e32 v204, v73
	v_exp_f32_e32 v202, v74
	v_exp_f32_e32 v120, v75
	ds_read_b64_tr_b16 v[72:73], v0 offset:38912
	ds_read_b64_tr_b16 v[74:75], v0 offset:39424
	ds_read_b64_tr_b16 v[80:81], v0 offset:31744
	ds_read_b64_tr_b16 v[82:83], v0 offset:32256
	v_exp_f32_e32 v210, v85
	v_cvt_pk_bf16_f32 v68, v196, v112
	v_cvt_pk_bf16_f32 v69, v198, v114
	v_cvt_pk_bf16_f32 v70, v200, v14
	v_cvt_pk_bf16_f32 v71, v12, v10
	v_pk_add_f32 v[216:217], v[124:125], v[200:201]
	v_exp_f32_e32 v208, v86
	s_waitcnt lgkmcnt(4)
; __device__ __forceinline__ void attn2_unit(bf16_t* Z, const bf16_t* Hb, const float* rc, const float* rs, LAS unsigned char* lds, int b, int h, int qblk) {
;     ...
;             a2_exp_pack(sa0, sa1, lsum, pa);
;             a2_pv(vb, pa, ot0, ot1);
;             a2_exp_pack(sb0, sb1, lsum, pb);
;             a2_pv(vb + 64 * 64, pb, ot0, ot1);
;         } else if (2 * kp <= cw) {
;             f32x16 sa0, sa1; bf16x8 pa[4];
;             a2_qk(kb, qf, cneg, sa0, sa1);
;             const float mt = a2_max(sa0, sa1);
;             if (kp == 0 || __builtin_amdgcn_ballot_w64(mt > 8.f) != 0ull) {
;                 const float delta = (kp == 0) ? mt : fmaxf(mt, 0.f), alpha = (kp == 0) ? 0.f : __builtin_amdgcn_exp2f(-delta);
;                 mrun += delta; lsum *= alpha;
; #pragma unroll
;                 for (int r = 0; r < 16; ++r) { ot0[r] *= alpha; ot1[r] *= alpha; sa0[r] -= delta; sa1[r] -= delta; cneg[r] = -mrun; }
;             }
;             a2_exp_pack(sa0, sa1, lsum, pa);
;             a2_pv(vb, pa, ot0, ot1);
;         }
;         __syncthreads();
;     }
	v_mfma_f32_32x32x16_bf16 v[16:31], v[64:67], v[68:71], v[16:31]
	v_add_f32_e64 v64, v216, v110
	v_add_f32_e64 v65, v217, v111
	v_add_f32_e64 v14, v210, v14
	v_add_f32_e64 v15, v211, v15
	v_exp_f32_e32 v214, v87
	v_exp_f32_e32 v116, v76
	v_exp_f32_e32 v118, v77
	v_exp_f32_e32 v98, v78
	v_exp_f32_e32 v96, v79
	s_waitcnt lgkmcnt(2)
	v_mfma_f32_32x32x16_bf16 v[32:47], v[72:75], v[68:71], v[32:47]
	v_add_f32_e64 v14, v14, v64
	v_add_f32_e64 v15, v15, v65
	ds_read_b64_tr_b16 v[64:65], v0 offset:39936
	ds_read_b64_tr_b16 v[66:67], v0 offset:40448
	v_exp_f32_e32 v122, v88
	v_pk_add_f32 v[12:13], v[208:209], v[12:13]
	v_pk_add_f32 v[68:69], v[214:215], v[10:11]
	v_pk_add_f32 v[14:15], v[12:13], v[14:15]
	v_cvt_pk_bf16_f32 v10, v206, v204
	v_cvt_pk_bf16_f32 v11, v202, v120
	v_cvt_pk_bf16_f32 v12, v116, v118
	v_cvt_pk_bf16_f32 v13, v98, v96
	v_pk_add_f32 v[14:15], v[68:69], v[14:15]
	v_pk_add_f32 v[68:69], v[122:123], v[206:207]
	s_waitcnt lgkmcnt(2)
	v_mfma_f32_32x32x16_bf16 v[16:31], v[80:83], v[10:13], v[16:31]
	v_add_f32_e64 v14, v68, v14
	v_add_f32_e64 v15, v69, v15
	ds_read_b64_tr_b16 v[68:69], v0 offset:32768
	ds_read_b64_tr_b16 v[70:71], v0 offset:33280
	v_exp_f32_e32 v126, v89
	v_exp_f32_e32 v104, v90
	v_cvt_pk_bf16_f32 v7, v2, v4
	v_exp_f32_e32 v212, v91
	v_cvt_pk_bf16_f32 v6, v6, v8
	s_waitcnt lgkmcnt(2)
	v_mfma_f32_32x32x16_bf16 v[32:47], v[64:67], v[10:13], v[32:47]
	ds_read_b64_tr_b16 v[2:3], v0 offset:40960
	ds_read_b64_tr_b16 v[4:5], v0 offset:41472
	ds_read_b64_tr_b16 v[10:11], v0 offset:33792
	ds_read_b64_tr_b16 v[12:13], v0 offset:34304
	v_cvt_pk_bf16_f32 v8, v124, v210
	v_cvt_pk_bf16_f32 v9, v208, v214
	v_pk_add_f32 v[72:73], v[126:127], v[204:205]
	v_pk_add_f32 v[64:65], v[104:105], v[202:203]
	v_pk_add_f32 v[14:15], v[72:73], v[14:15]
	v_exp_f32_e32 v106, v92
	s_waitcnt lgkmcnt(4)
	v_mfma_f32_32x32x16_bf16 v[16:31], v[68:71], v[6:9], v[16:31]
	v_add_f32_e64 v14, v64, v14
	v_add_f32_e64 v15, v65, v15
	v_add_f32_e64 v64, v212, v120
	v_add_f32_e64 v65, v213, v121
	v_exp_f32_e32 v108, v93
	v_exp_f32_e32 v102, v94
	v_exp_f32_e32 v100, v95
	v_pk_add_f32 v[14:15], v[64:65], v[14:15]
	ds_read_b64_tr_b16 v[64:65], v0 offset:41984
	ds_read_b64_tr_b16 v[66:67], v0 offset:42496
	s_waitcnt lgkmcnt(4)
	v_mfma_f32_32x32x16_bf16 v[32:47], v[2:5], v[6:9], v[32:47]
	v_add_f32_e64 v2, v106, v116
	v_add_f32_e64 v3, v107, v117
	v_cvt_pk_bf16_f32 v4, v106, v108
	v_add_f32_e64 v6, v2, v14
	v_add_f32_e64 v7, v3, v15
	v_cvt_pk_bf16_f32 v2, v122, v126
	v_cvt_pk_bf16_f32 v3, v104, v212
	v_cvt_pk_bf16_f32 v5, v102, v100
	v_pk_add_f32 v[8:9], v[108:109], v[118:119]
	v_mov_b32_e32 v14, v55
	s_waitcnt lgkmcnt(2)
	v_mfma_f32_32x32x16_bf16 v[16:31], v[10:13], v[2:5], v[16:31]
	v_add_f32_e64 v6, v8, v6
	v_add_f32_e64 v7, v9, v7
	v_add_f32_e64 v8, v102, v98
	v_add_f32_e64 v9, v103, v99
	v_mov_b32_e32 v10, v59
	v_pk_add_f32 v[6:7], v[8:9], v[6:7]
	v_pk_add_f32 v[8:9], v[100:101], v[96:97]
	v_mov_b32_e32 v11, v58
	v_pk_add_f32 v[6:7], v[8:9], v[6:7]
	s_waitcnt lgkmcnt(0)
	v_mfma_f32_32x32x16_bf16 v[32:47], v[64:67], v[2:5], v[32:47]
	v_add_f32_e32 v0, v169, v7
	v_add_f32_e32 v0, v6, v0
	s_add_i32 s35, s35, 1
	s_add_i32 s56, s56, 2
	s_add_i32 s6, s46, s35
	v_lshl_add_u64 v[174:175], v[174:175], 0, v[170:171]
	v_lshl_add_u64 v[176:177], v[176:177], 0, s[20:21]
	v_lshl_add_u64 v[178:179], v[178:179], 0, s[20:21]
	v_lshl_add_u64 v[182:183], v[182:183], 0, v[180:181]
	v_lshl_add_u64 v[186:187], v[186:187], 0, v[184:185]
	s_cmp_lg_u32 s6, 1
	v_lshl_add_u64 v[190:191], v[190:191], 0, v[188:189]
	s_waitcnt vmcnt(0) lgkmcnt(0)
	s_barrier
	s_cbranch_scc0 .Lattn_exit_1
	v_mov_b32_e32 v169, v0
	s_bitcmp1_b32 s35, 0
	s_cselect_b32 s6, 0, 0xa800
	s_cmp_ge_u32 s35, s42
	s_cbranch_scc0 .LBB0_856
	s_branch .LBB0_859

; #define LAS __attribute__((address_space(3)))
; __device__ __forceinline__ void a2_qk(const LAS unsigned char* kb, const bf16x8 (&qf)[6], const f32x16& cneg, f32x16& st0, f32x16& st1) {
;     { const bf16x8 a0 = *(const LAS bf16x8*)(kb), a1 = *(const LAS bf16x8*)(kb + 32 * AT_KROW);
;       st0 = __builtin_amdgcn_mfma_f32_32x32x16_bf16(a0, qf[0], cneg, 0, 0, 0); st1 = __builtin_amdgcn_mfma_f32_32x32x16_bf16(a1, qf[0], cneg, 0, 0, 0); }
; #pragma unroll
;     for (int s = 1; s < 6; ++s) { const bf16x8 a0 = *(const LAS bf16x8*)(kb + s * 32), a1 = *(const LAS bf16x8*)(kb + 32 * AT_KROW + s * 32);
;         st0 = __builtin_amdgcn_mfma_f32_32x32x16_bf16(a0, qf[s], st0, 0, 0, 0); st1 = __builtin_amdgcn_mfma_f32_32x32x16_bf16(a1, qf[s], st1, 0, 0, 0); }
; }
; __device__ __forceinline__ void attn2_unit(bf16_t* Z, const bf16_t* Hb, const float* rc, const float* rs, LAS unsigned char* lds, int b, int h, int qblk) {
;     ...
;         if (2 * kp + 1 <= cw) {
;             f32x16 sa0, sa1, sb0, sb1; bf16x8 pa[4], pb[4];
;             __builtin_amdgcn_s_setprio(1);
;             a2_qk(kb, qf, cneg, sa0, sa1);
;             a2_qk(kb + 64 * AT_KROW, qf, cneg, sb0, sb1);
;             __builtin_amdgcn_s_setprio(0);
;             const float mt = fmaxf(a2_max(sa0, sa1), a2_max(sb0, sb1));
;             if (kp == 0 || __builtin_amdgcn_ballot_w64(mt > 8.f) != 0ull) {
;                 const float delta = (kp == 0) ? mt : fmaxf(mt, 0.f), alpha = (kp == 0) ? 0.f : __builtin_amdgcn_exp2f(-delta);
;                 mrun += delta; lsum *= alpha;
.LBB0_2235:
	s_andn2_b64 vcc, exec, s[6:7]
	s_cbranch_vccnz .LBB0_2244
	s_setprio 1
	v_add_u32_e32 v0, v3, v156
	ds_read_b128 v[4:7], v0
	ds_read_b128 v[8:11], v0 offset:6656
	ds_read_b128 v[12:15], v0 offset:32
	ds_read_b128 v[248:251], v0 offset:6688
	v_mov_b64_e32 v[94:95], v[62:63]
	v_mov_b64_e32 v[92:93], v[60:61]
	v_mov_b64_e32 v[90:91], v[58:59]
	v_mov_b64_e32 v[88:89], v[56:57]
	v_mov_b64_e32 v[86:87], v[54:55]
	v_mov_b64_e32 v[84:85], v[52:53]
	v_mov_b64_e32 v[82:83], v[50:51]
	v_mov_b64_e32 v[80:81], v[48:49]
	s_waitcnt lgkmcnt(3)
	v_mfma_f32_32x32x16_bf16 v[112:127], v[4:7], v[128:131], v[48:63]
	ds_read_b128 v[252:255], v0 offset:64
	s_waitcnt lgkmcnt(3)
	v_mfma_f32_32x32x16_bf16 v[96:111], v[8:11], v[128:131], v[48:63]
	ds_read_b128 v[4:7], v0 offset:6720
	s_waitcnt lgkmcnt(3)
	v_mfma_f32_32x32x16_bf16 v[112:127], v[12:15], v[132:135], v[112:127]
	ds_read_b128 v[8:11], v0 offset:96
	s_waitcnt lgkmcnt(3)
	v_mfma_f32_32x32x16_bf16 v[96:111], v[248:251], v[132:135], v[96:111]
	ds_read_b128 v[12:15], v0 offset:6752
	s_waitcnt lgkmcnt(3)
	v_mfma_f32_32x32x16_bf16 v[112:127], v[252:255], v[136:139], v[112:127]
	ds_read_b128 v[248:251], v0 offset:128
	s_waitcnt lgkmcnt(3)
	v_mfma_f32_32x32x16_bf16 v[96:111], v[4:7], v[136:139], v[96:111]
	ds_read_b128 v[252:255], v0 offset:6784
	s_waitcnt lgkmcnt(3)
	v_mfma_f32_32x32x16_bf16 v[112:127], v[8:11], v[140:143], v[112:127]
	ds_read_b128 v[4:7], v0 offset:160
	s_waitcnt lgkmcnt(3)
	v_mfma_f32_32x32x16_bf16 v[96:111], v[12:15], v[140:143], v[96:111]
	ds_read_b128 v[8:11], v0 offset:13312
	s_waitcnt lgkmcnt(3)
	v_mfma_f32_32x32x16_bf16 v[112:127], v[248:251], v[144:147], v[112:127]
	ds_read_b128 v[12:15], v0 offset:6816
	s_waitcnt lgkmcnt(3)
	v_mfma_f32_32x32x16_bf16 v[96:111], v[252:255], v[144:147], v[96:111]
	ds_read_b128 v[248:251], v0 offset:19968
	s_waitcnt lgkmcnt(3)
	v_mfma_f32_32x32x16_bf16 v[112:127], v[4:7], v[148:151], v[112:127]
	ds_read_b128 v[252:255], v0 offset:13344
	s_waitcnt lgkmcnt(3)
	v_mfma_f32_32x32x16_bf16 v[64:79], v[8:11], v[128:131], v[48:63]
	ds_read_b128 v[4:7], v0 offset:20000
	s_waitcnt lgkmcnt(3)
	v_mfma_f32_32x32x16_bf16 v[96:111], v[12:15], v[148:151], v[96:111]
	ds_read_b128 v[8:11], v0 offset:13376
	s_waitcnt lgkmcnt(3)
	v_mfma_f32_32x32x16_bf16 v[80:95], v[248:251], v[128:131], v[80:95]
	ds_read_b128 v[12:15], v0 offset:20032
	s_waitcnt lgkmcnt(3)
	v_mfma_f32_32x32x16_bf16 v[64:79], v[252:255], v[132:135], v[64:79]
	ds_read_b128 v[248:251], v0 offset:13408
	s_waitcnt lgkmcnt(3)
	v_mfma_f32_32x32x16_bf16 v[80:95], v[4:7], v[132:135], v[80:95]
	ds_read_b128 v[252:255], v0 offset:20064
	s_waitcnt lgkmcnt(3)
	v_mfma_f32_32x32x16_bf16 v[64:79], v[8:11], v[136:139], v[64:79]
	ds_read_b128 v[4:7], v0 offset:13440
	s_waitcnt lgkmcnt(3)
	v_mfma_f32_32x32x16_bf16 v[80:95], v[12:15], v[136:139], v[80:95]
	ds_read_b128 v[8:11], v0 offset:20096
	s_waitcnt lgkmcnt(3)
	v_mfma_f32_32x32x16_bf16 v[64:79], v[248:251], v[140:143], v[64:79]
	ds_read_b128 v[12:15], v0 offset:13472
	s_waitcnt lgkmcnt(3)
	v_mfma_f32_32x32x16_bf16 v[80:95], v[252:255], v[140:143], v[80:95]
	ds_read_b128 v[248:251], v0 offset:20128
	s_waitcnt lgkmcnt(3)
	v_mfma_f32_32x32x16_bf16 v[64:79], v[4:7], v[144:147], v[64:79]
	s_waitcnt lgkmcnt(2)
	v_mfma_f32_32x32x16_bf16 v[80:95], v[8:11], v[144:147], v[80:95]
	s_waitcnt lgkmcnt(1)
	v_mfma_f32_32x32x16_bf16 v[64:79], v[12:15], v[148:151], v[64:79]
	s_waitcnt lgkmcnt(0)
	v_mfma_f32_32x32x16_bf16 v[80:95], v[248:251], v[148:151], v[80:95]
	s_nop 0
	v_max_f32_e32 v0, v96, v96
	v_max_f32_e32 v3, v112, v112
	v_max_f32_e32 v0, v3, v0
	s_nop 7
	v_max_f32_e32 v3, v80, v80
	v_max_f32_e32 v4, v64, v64
	v_max_f32_e32 v3, v4, v3
	v_max3_f32 v3, v3, v65, v81
	v_max3_f32 v3, v3, v66, v82
	v_max3_f32 v0, v0, v113, v97
	v_max3_f32 v3, v3, v67, v83
	v_max3_f32 v0, v0, v114, v98
	v_max3_f32 v3, v3, v68, v84
	v_max3_f32 v0, v0, v115, v99
	v_max3_f32 v3, v3, v69, v85
	v_max3_f32 v0, v0, v116, v100
	v_max3_f32 v3, v3, v70, v86
	v_max3_f32 v0, v0, v117, v101
	v_max3_f32 v3, v3, v71, v87
	v_max3_f32 v0, v0, v118, v102
	v_max3_f32 v3, v3, v72, v88
	v_max3_f32 v0, v0, v119, v103
	v_max3_f32 v3, v3, v73, v89
	v_max3_f32 v0, v0, v120, v104
	v_max3_f32 v3, v3, v74, v90
	v_max3_f32 v0, v0, v121, v105
	v_max3_f32 v3, v3, v75, v91
	v_max3_f32 v0, v0, v122, v106
	v_max3_f32 v3, v3, v76, v92
	v_max3_f32 v0, v0, v123, v107
	v_max3_f32 v3, v3, v77, v93
	v_max3_f32 v0, v0, v124, v108
	v_max3_f32 v3, v3, v78, v94
	v_max3_f32 v3, v3, v79, v95
	v_max3_f32 v0, v0, v125, v109
	v_max3_f32 v0, v0, v126, v110
	v_max3_f32 v0, v0, v127, v111
	s_cmp_eq_u32 s47, 1
	v_max_f32_e32 v3, v3, v0
	v_mov_b32_e32 v4, v3
	v_mov_b32_e32 v5, v3
	s_cselect_b64 s[30:31], -1, 0
	s_cmp_lg_u32 s47, 1
	v_permlane32_swap_b32_e32 v4, v5
	v_max_f32_e32 v3, v4, v5
	s_cbranch_scc0 .LBB0_2246
	v_cmp_lt_f32_e32 vcc, s41, v3
	s_mov_b64 s[24:25], 0
	s_mov_b64 s[6:7], 0
	s_cbranch_vccz .LBB0_2239
	v_max_f32_e32 v0, v3, v3
	v_max_f32_e32 v0, 0, v0
	s_mov_b64 s[6:7], -1

; #define LAS __attribute__((address_space(3)))
; __device__ __forceinline__ void a2_exp_pack(f32x16& st0, f32x16& st1, float& lsum, bf16x8 (&pf)[4]) {
;     float ps = 0.f;
; #pragma unroll
;     for (int r = 0; r < 16; ++r) { st0[r] = __builtin_amdgcn_exp2f(st0[r]); st1[r] = __builtin_amdgcn_exp2f(st1[r]); ps += st0[r] + st1[r]; }
;     lsum += ps;
;     u32x4 w;
;     w.x = cvtpk2(st0[0], st0[1]); w.y = cvtpk2(st0[2], st0[3]); w.z = cvtpk2(st0[4], st0[5]); w.w = cvtpk2(st0[6], st0[7]); pf[0] = __builtin_bit_cast(bf16x8, w);
;     w.x = cvtpk2(st0[8], st0[9]); w.y = cvtpk2(st0[10], st0[11]); w.z = cvtpk2(st0[12], st0[13]); w.w = cvtpk2(st0[14], st0[15]); pf[1] = __builtin_bit_cast(bf16x8, w);
;     w.x = cvtpk2(st1[0], st1[1]); w.y = cvtpk2(st1[2], st1[3]); w.z = cvtpk2(st1[4], st1[5]); w.w = cvtpk2(st1[6], st1[7]); pf[2] = __builtin_bit_cast(bf16x8, w);
;     w.x = cvtpk2(st1[8], st1[9]); w.y = cvtpk2(st1[10], st1[11]); w.z = cvtpk2(st1[12], st1[13]); w.w = cvtpk2(st1[14], st1[15]); pf[3] = __builtin_bit_cast(bf16x8, w);
; }
; __device__ __forceinline__ void a2_pv(const LAS unsigned char* vb, const bf16x8 (&pf)[4], f32x16& ot0, f32x16& ot1) {
; #pragma unroll
;     for (int s = 0; s < 4; ++s) {
;         const s16x4 a00 = __builtin_bit_cast(s16x4, __builtin_amdgcn_ds_read_tr16_b64_v4i16((LAS s16x4*)(vb + (16 * s) * 64)));
;         const s16x4 a01 = __builtin_bit_cast(s16x4, __builtin_amdgcn_ds_read_tr16_b64_v4i16((LAS s16x4*)(vb + (16 * s + 8) * 64)));
;         const s16x4 a10 = __builtin_bit_cast(s16x4, __builtin_amdgcn_ds_read_tr16_b64_v4i16((LAS s16x4*)(vb + 8192 + (16 * s) * 64)));
;         const s16x4 a11 = __builtin_bit_cast(s16x4, __builtin_amdgcn_ds_read_tr16_b64_v4i16((LAS s16x4*)(vb + 8192 + (16 * s + 8) * 64)));
;         const bf16x8 va0 = (bf16x8){a00[0], a00[1], a00[2], a00[3], a01[0], a01[1], a01[2], a01[3]};
;         const bf16x8 va1 = (bf16x8){a10[0], a10[1], a10[2], a10[3], a11[0], a11[1], a11[2], a11[3]};
; __device__ __forceinline__ void attn2_unit(bf16_t* Z, const bf16_t* Hb, const float* rc, const float* rs, LAS unsigned char* lds, int b, int h, int qblk) {
;     ...
;             a2_exp_pack(sa0, sa1, lsum, pa);
;             a2_pv(vb, pa, ot0, ot1);
;             a2_exp_pack(sb0, sb1, lsum, pb);
;             a2_pv(vb + 64 * 64, pb, ot0, ot1);
.LBB0_2243:
	s_setprio 0
	v_add_u32_e32 v0, v2, v218
	v_exp_f32_e32 v199, v112
	v_exp_f32_e32 v7, v96
	v_exp_f32_e32 v113, v113
	v_exp_f32_e32 v9, v97
	v_exp_f32_e32 v201, v114
	v_exp_f32_e32 v3, v98
	v_exp_f32_e32 v115, v115
	v_exp_f32_e32 v5, v99
	v_exp_f32_e32 v203, v116
	v_exp_f32_e32 v15, v117
	v_exp_f32_e32 v13, v118
	v_exp_f32_e32 v11, v119
	s_waitcnt vmcnt(0)
	ds_read_b64_tr_b16 v[96:97], v0 offset:26624
	ds_read_b64_tr_b16 v[98:99], v0 offset:27136
	ds_read_b64_tr_b16 v[214:215], v0 offset:34816
	ds_read_b64_tr_b16 v[216:217], v0 offset:35328
	ds_read_b64_tr_b16 v[220:221], v0 offset:27648
	ds_read_b64_tr_b16 v[222:223], v0 offset:28160
	v_cvt_pk_bf16_f32 v210, v199, v113
	v_cvt_pk_bf16_f32 v211, v201, v115
	v_cvt_pk_bf16_f32 v212, v203, v15
	v_cvt_pk_bf16_f32 v213, v13, v11
	v_exp_f32_e32 v209, v120
	v_exp_f32_e32 v207, v121
	s_waitcnt lgkmcnt(4)
	v_mfma_f32_32x32x16_bf16 v[16:31], v[96:99], v[210:213], v[16:31]
	v_exp_f32_e32 v205, v122
	v_exp_f32_e32 v121, v123
	v_exp_f32_e32 v117, v124
	ds_read_b64_tr_b16 v[224:225], v0 offset:35840
	ds_read_b64_tr_b16 v[226:227], v0 offset:36352
	v_exp_f32_e32 v119, v125
	v_exp_f32_e32 v99, v126
	v_exp_f32_e32 v97, v127
	s_waitcnt lgkmcnt(4)
	v_mfma_f32_32x32x16_bf16 v[32:47], v[214:217], v[210:213], v[32:47]
	v_cvt_pk_bf16_f32 v228, v209, v207
	v_cvt_pk_bf16_f32 v229, v205, v121
	v_cvt_pk_bf16_f32 v230, v117, v119
	v_cvt_pk_bf16_f32 v231, v99, v97
	v_exp_f32_e32 v125, v100
	v_exp_f32_e32 v213, v101
	v_exp_f32_e32 v211, v102
	s_waitcnt lgkmcnt(2)
	v_mfma_f32_32x32x16_bf16 v[16:31], v[220:223], v[228:231], v[16:31]
	v_exp_f32_e32 v217, v103
	ds_read_b64_tr_b16 v[220:221], v0 offset:28672
	ds_read_b64_tr_b16 v[222:223], v0 offset:29184
	v_cvt_pk_bf16_f32 v100, v7, v9
	v_cvt_pk_bf16_f32 v101, v3, v5
	v_cvt_pk_bf16_f32 v102, v125, v213
	v_cvt_pk_bf16_f32 v103, v211, v217
	v_exp_f32_e32 v123, v104
	s_waitcnt lgkmcnt(2)
	v_mfma_f32_32x32x16_bf16 v[32:47], v[224:227], v[228:231], v[32:47]
	ds_read_b64_tr_b16 v[224:225], v0 offset:36864
	ds_read_b64_tr_b16 v[226:227], v0 offset:37376
	ds_read_b64_tr_b16 v[228:229], v0 offset:29696
	ds_read_b64_tr_b16 v[230:231], v0 offset:30208
	v_exp_f32_e32 v127, v105
	v_exp_f32_e32 v105, v106
	v_exp_f32_e32 v215, v107
	v_exp_f32_e32 v107, v108
	v_exp_f32_e32 v109, v109
	v_exp_f32_e32 v198, v64
	s_waitcnt lgkmcnt(4)
	v_mfma_f32_32x32x16_bf16 v[16:31], v[220:223], v[100:103], v[16:31]
	ds_read_b64_tr_b16 v[220:221], v0 offset:37888
	ds_read_b64_tr_b16 v[222:223], v0 offset:38400
	v_exp_f32_e32 v6, v80
	v_exp_f32_e32 v112, v65
	v_exp_f32_e32 v8, v81
	v_exp_f32_e32 v200, v66
	v_exp_f32_e32 v2, v82
	v_exp_f32_e32 v114, v67
	s_waitcnt lgkmcnt(4)
	v_mfma_f32_32x32x16_bf16 v[32:47], v[224:227], v[100:103], v[32:47]
	v_exp_f32_e32 v103, v110
	v_exp_f32_e32 v101, v111
	v_exp_f32_e32 v4, v83
	v_cvt_pk_bf16_f32 v224, v123, v127
	v_cvt_pk_bf16_f32 v225, v105, v215
	v_cvt_pk_bf16_f32 v226, v107, v109
	v_cvt_pk_bf16_f32 v227, v103, v101
	v_pk_add_f32 v[64:65], v[6:7], v[198:199]
	v_pk_add_f32 v[66:67], v[8:9], v[112:113]
	s_waitcnt lgkmcnt(2)
	v_mfma_f32_32x32x16_bf16 v[16:31], v[228:231], v[224:227], v[16:31]
	v_add_f32_e64 v64, v64, 0
	v_add_f32_e64 v65, v65, 0
	v_exp_f32_e32 v202, v68
	v_pk_add_f32 v[64:65], v[66:67], v[64:65]
	v_pk_add_f32 v[66:67], v[2:3], v[200:201]
	v_exp_f32_e32 v14, v69
	v_pk_add_f32 v[64:65], v[66:67], v[64:65]
	v_pk_add_f32 v[66:67], v[4:5], v[114:115]
	s_waitcnt lgkmcnt(0)
	v_mfma_f32_32x32x16_bf16 v[32:47], v[220:223], v[224:227], v[32:47]
	v_add_f32_e64 v110, v66, v64
	v_add_f32_e64 v111, v67, v65
	v_exp_f32_e32 v12, v70
	v_exp_f32_e32 v10, v71
	ds_read_b64_tr_b16 v[64:65], v0 offset:30720
	ds_read_b64_tr_b16 v[66:67], v0 offset:31232
	v_exp_f32_e32 v124, v84
	v_exp_f32_e32 v208, v72
	v_exp_f32_e32 v206, v73
	v_exp_f32_e32 v204, v74
	v_exp_f32_e32 v120, v75
	ds_read_b64_tr_b16 v[72:73], v0 offset:38912
	ds_read_b64_tr_b16 v[74:75], v0 offset:39424
	ds_read_b64_tr_b16 v[80:81], v0 offset:31744
	ds_read_b64_tr_b16 v[82:83], v0 offset:32256
	v_exp_f32_e32 v212, v85
	v_cvt_pk_bf16_f32 v68, v198, v112
	v_cvt_pk_bf16_f32 v69, v200, v114
	v_cvt_pk_bf16_f32 v70, v202, v14
	v_cvt_pk_bf16_f32 v71, v12, v10
	v_pk_add_f32 v[220:221], v[124:125], v[202:203]
	v_exp_f32_e32 v210, v86
	s_waitcnt lgkmcnt(4)
; __device__ __forceinline__ void attn2_unit(bf16_t* Z, const bf16_t* Hb, const float* rc, const float* rs, LAS unsigned char* lds, int b, int h, int qblk) {
;     ...
;             a2_exp_pack(sa0, sa1, lsum, pa);
;             a2_pv(vb, pa, ot0, ot1);
;             a2_exp_pack(sb0, sb1, lsum, pb);
;             a2_pv(vb + 64 * 64, pb, ot0, ot1);
;         } else if (2 * kp <= cw) {
;             f32x16 sa0, sa1; bf16x8 pa[4];
;             a2_qk(kb, qf, cneg, sa0, sa1);
;             const float mt = a2_max(sa0, sa1);
;             if (kp == 0 || __builtin_amdgcn_ballot_w64(mt > 8.f) != 0ull) {
;                 const float delta = (kp == 0) ? mt : fmaxf(mt, 0.f), alpha = (kp == 0) ? 0.f : __builtin_amdgcn_exp2f(-delta);
;                 mrun += delta; lsum *= alpha;
; #pragma unroll
;                 for (int r = 0; r < 16; ++r) { ot0[r] *= alpha; ot1[r] *= alpha; sa0[r] -= delta; sa1[r] -= delta; cneg[r] = -mrun; }
;             }
;             a2_exp_pack(sa0, sa1, lsum, pa);
;             a2_pv(vb, pa, ot0, ot1);
;         }
;         __syncthreads();
;     }
	v_mfma_f32_32x32x16_bf16 v[16:31], v[64:67], v[68:71], v[16:31]
	v_add_f32_e64 v64, v220, v110
	v_add_f32_e64 v65, v221, v111
	v_add_f32_e64 v14, v212, v14
	v_add_f32_e64 v15, v213, v15
	v_exp_f32_e32 v216, v87
	v_exp_f32_e32 v116, v76
	v_exp_f32_e32 v118, v77
	v_exp_f32_e32 v98, v78
	v_exp_f32_e32 v96, v79
	s_waitcnt lgkmcnt(2)
	v_mfma_f32_32x32x16_bf16 v[32:47], v[72:75], v[68:71], v[32:47]
	v_add_f32_e64 v14, v14, v64
	v_add_f32_e64 v15, v15, v65
	ds_read_b64_tr_b16 v[64:65], v0 offset:39936
	ds_read_b64_tr_b16 v[66:67], v0 offset:40448
	v_exp_f32_e32 v122, v88
	v_pk_add_f32 v[12:13], v[210:211], v[12:13]
	v_pk_add_f32 v[68:69], v[216:217], v[10:11]
	v_pk_add_f32 v[14:15], v[12:13], v[14:15]
	v_cvt_pk_bf16_f32 v10, v208, v206
	v_cvt_pk_bf16_f32 v11, v204, v120
	v_cvt_pk_bf16_f32 v12, v116, v118
	v_cvt_pk_bf16_f32 v13, v98, v96
	v_pk_add_f32 v[14:15], v[68:69], v[14:15]
	v_pk_add_f32 v[68:69], v[122:123], v[208:209]
	s_waitcnt lgkmcnt(2)
	v_mfma_f32_32x32x16_bf16 v[16:31], v[80:83], v[10:13], v[16:31]
	v_add_f32_e64 v14, v68, v14
	v_add_f32_e64 v15, v69, v15
	ds_read_b64_tr_b16 v[68:69], v0 offset:32768
	ds_read_b64_tr_b16 v[70:71], v0 offset:33280
	v_exp_f32_e32 v126, v89
	v_exp_f32_e32 v104, v90
	v_cvt_pk_bf16_f32 v7, v2, v4
	v_exp_f32_e32 v214, v91
	v_cvt_pk_bf16_f32 v6, v6, v8
	s_waitcnt lgkmcnt(2)
	v_mfma_f32_32x32x16_bf16 v[32:47], v[64:67], v[10:13], v[32:47]
	ds_read_b64_tr_b16 v[2:3], v0 offset:40960
	ds_read_b64_tr_b16 v[4:5], v0 offset:41472
	ds_read_b64_tr_b16 v[10:11], v0 offset:33792
	ds_read_b64_tr_b16 v[12:13], v0 offset:34304
	v_cvt_pk_bf16_f32 v8, v124, v212
	v_cvt_pk_bf16_f32 v9, v210, v216
	v_pk_add_f32 v[72:73], v[126:127], v[206:207]
	v_pk_add_f32 v[64:65], v[104:105], v[204:205]
	v_pk_add_f32 v[14:15], v[72:73], v[14:15]
	v_exp_f32_e32 v106, v92
	s_waitcnt lgkmcnt(4)
	v_mfma_f32_32x32x16_bf16 v[16:31], v[68:71], v[6:9], v[16:31]
	v_add_f32_e64 v14, v64, v14
	v_add_f32_e64 v15, v65, v15
	v_add_f32_e64 v64, v214, v120
	v_add_f32_e64 v65, v215, v121
	v_exp_f32_e32 v108, v93
	v_exp_f32_e32 v102, v94
	v_exp_f32_e32 v100, v95
	v_pk_add_f32 v[14:15], v[64:65], v[14:15]
	ds_read_b64_tr_b16 v[64:65], v0 offset:41984
	ds_read_b64_tr_b16 v[66:67], v0 offset:42496
	s_waitcnt lgkmcnt(4)
	v_mfma_f32_32x32x16_bf16 v[32:47], v[2:5], v[6:9], v[32:47]
	v_add_f32_e64 v2, v106, v116
	v_add_f32_e64 v3, v107, v117
	v_cvt_pk_bf16_f32 v4, v106, v108
	v_add_f32_e64 v6, v2, v14
	v_add_f32_e64 v7, v3, v15
	v_cvt_pk_bf16_f32 v2, v122, v126
	v_cvt_pk_bf16_f32 v3, v104, v214
	v_cvt_pk_bf16_f32 v5, v102, v100
	v_pk_add_f32 v[8:9], v[108:109], v[118:119]
	v_mov_b32_e32 v14, v55
	s_waitcnt lgkmcnt(2)
	v_mfma_f32_32x32x16_bf16 v[16:31], v[10:13], v[2:5], v[16:31]
	v_add_f32_e64 v6, v8, v6
	v_add_f32_e64 v7, v9, v7
	v_add_f32_e64 v8, v102, v98
	v_add_f32_e64 v9, v103, v99
	v_mov_b32_e32 v10, v59
	v_pk_add_f32 v[6:7], v[8:9], v[6:7]
	v_pk_add_f32 v[8:9], v[100:101], v[96:97]
	v_mov_b32_e32 v11, v58
	v_pk_add_f32 v[6:7], v[8:9], v[6:7]
	s_waitcnt lgkmcnt(0)
	v_mfma_f32_32x32x16_bf16 v[32:47], v[64:67], v[2:5], v[32:47]
	v_add_f32_e32 v0, v169, v7
	v_add_f32_e32 v0, v6, v0
	s_add_i32 s47, s47, 1
	s_add_i32 s48, s48, 2
	s_add_i32 s6, s37, s47
	v_lshl_add_u64 v[176:177], v[176:177], 0, v[174:175]
	v_lshl_add_u64 v[178:179], v[178:179], 0, s[18:19]
	v_lshl_add_u64 v[180:181], v[180:181], 0, s[18:19]
	v_lshl_add_u64 v[184:185], v[184:185], 0, v[182:183]
	v_lshl_add_u64 v[188:189], v[188:189], 0, v[186:187]
	s_cmp_lg_u32 s6, 1
	v_lshl_add_u64 v[194:195], v[194:195], 0, v[190:191]
	s_waitcnt vmcnt(0) lgkmcnt(0)
	s_barrier
	s_cbranch_scc0 .Lattn_exit_2
	v_mov_b32_e32 v169, v0
	s_bitcmp1_b32 s47, 0
	s_cselect_b32 s6, 0, 0xa800
	s_cmp_ge_u32 s47, s34
	s_cbranch_scc0 .LBB0_2221
	s_branch .LBB0_2224

; #define LAS __attribute__((address_space(3)))
; __device__ __forceinline__ void a2_qk(const LAS unsigned char* kb, const bf16x8 (&qf)[6], const f32x16& cneg, f32x16& st0, f32x16& st1) {
;     { const bf16x8 a0 = *(const LAS bf16x8*)(kb), a1 = *(const LAS bf16x8*)(kb + 32 * AT_KROW);
;       st0 = __builtin_amdgcn_mfma_f32_32x32x16_bf16(a0, qf[0], cneg, 0, 0, 0); st1 = __builtin_amdgcn_mfma_f32_32x32x16_bf16(a1, qf[0], cneg, 0, 0, 0); }
; #pragma unroll
;     for (int s = 1; s < 6; ++s) { const bf16x8 a0 = *(const LAS bf16x8*)(kb + s * 32), a1 = *(const LAS bf16x8*)(kb + 32 * AT_KROW + s * 32);
;         st0 = __builtin_amdgcn_mfma_f32_32x32x16_bf16(a0, qf[s], st0, 0, 0, 0); st1 = __builtin_amdgcn_mfma_f32_32x32x16_bf16(a1, qf[s], st1, 0, 0, 0); }
; }
; __device__ __forceinline__ void attn2_unit(bf16_t* Z, const bf16_t* Hb, const float* rc, const float* rs, LAS unsigned char* lds, int b, int h, int qblk) {
;     ...
;         if (2 * kp + 1 <= cw) {
;             f32x16 sa0, sa1, sb0, sb1; bf16x8 pa[4], pb[4];
;             __builtin_amdgcn_s_setprio(1);
;             a2_qk(kb, qf, cneg, sa0, sa1);
;             a2_qk(kb + 64 * AT_KROW, qf, cneg, sb0, sb1);
;             __builtin_amdgcn_s_setprio(0);
;             const float mt = fmaxf(a2_max(sa0, sa1), a2_max(sb0, sb1));
;             if (kp == 0 || __builtin_amdgcn_ballot_w64(mt > 8.f) != 0ull) {
;                 const float delta = (kp == 0) ? mt : fmaxf(mt, 0.f), alpha = (kp == 0) ? 0.f : __builtin_amdgcn_exp2f(-delta);
;                 mrun += delta; lsum *= alpha;
.LBB0_2281:
	s_andn2_b64 vcc, exec, s[6:7]
	s_cbranch_vccnz .LBB0_2290
	s_setprio 1
	v_add_u32_e32 v0, v3, v156
	ds_read_b128 v[4:7], v0
	ds_read_b128 v[8:11], v0 offset:6656
	ds_read_b128 v[12:15], v0 offset:32
	ds_read_b128 v[248:251], v0 offset:6688
	v_mov_b64_e32 v[94:95], v[62:63]
	v_mov_b64_e32 v[92:93], v[60:61]
	v_mov_b64_e32 v[90:91], v[58:59]
	v_mov_b64_e32 v[88:89], v[56:57]
	v_mov_b64_e32 v[86:87], v[54:55]
	v_mov_b64_e32 v[84:85], v[52:53]
	v_mov_b64_e32 v[82:83], v[50:51]
	v_mov_b64_e32 v[80:81], v[48:49]
	s_waitcnt lgkmcnt(3)
	v_mfma_f32_32x32x16_bf16 v[112:127], v[4:7], v[128:131], v[48:63]
	ds_read_b128 v[252:255], v0 offset:64
	s_waitcnt lgkmcnt(3)
	v_mfma_f32_32x32x16_bf16 v[96:111], v[8:11], v[128:131], v[48:63]
	ds_read_b128 v[4:7], v0 offset:6720
	s_waitcnt lgkmcnt(3)
	v_mfma_f32_32x32x16_bf16 v[112:127], v[12:15], v[132:135], v[112:127]
	ds_read_b128 v[8:11], v0 offset:96
	s_waitcnt lgkmcnt(3)
	v_mfma_f32_32x32x16_bf16 v[96:111], v[248:251], v[132:135], v[96:111]
	ds_read_b128 v[12:15], v0 offset:6752
	s_waitcnt lgkmcnt(3)
	v_mfma_f32_32x32x16_bf16 v[112:127], v[252:255], v[136:139], v[112:127]
	ds_read_b128 v[248:251], v0 offset:128
	s_waitcnt lgkmcnt(3)
	v_mfma_f32_32x32x16_bf16 v[96:111], v[4:7], v[136:139], v[96:111]
	ds_read_b128 v[252:255], v0 offset:6784
	s_waitcnt lgkmcnt(3)
	v_mfma_f32_32x32x16_bf16 v[112:127], v[8:11], v[140:143], v[112:127]
	ds_read_b128 v[4:7], v0 offset:160
	s_waitcnt lgkmcnt(3)
	v_mfma_f32_32x32x16_bf16 v[96:111], v[12:15], v[140:143], v[96:111]
	ds_read_b128 v[8:11], v0 offset:13312
	s_waitcnt lgkmcnt(3)
	v_mfma_f32_32x32x16_bf16 v[112:127], v[248:251], v[144:147], v[112:127]
	ds_read_b128 v[12:15], v0 offset:6816
	s_waitcnt lgkmcnt(3)
	v_mfma_f32_32x32x16_bf16 v[96:111], v[252:255], v[144:147], v[96:111]
	ds_read_b128 v[248:251], v0 offset:19968
	s_waitcnt lgkmcnt(3)
	v_mfma_f32_32x32x16_bf16 v[112:127], v[4:7], v[148:151], v[112:127]
	ds_read_b128 v[252:255], v0 offset:13344
	s_waitcnt lgkmcnt(3)
	v_mfma_f32_32x32x16_bf16 v[64:79], v[8:11], v[128:131], v[48:63]
	ds_read_b128 v[4:7], v0 offset:20000
	s_waitcnt lgkmcnt(3)
	v_mfma_f32_32x32x16_bf16 v[96:111], v[12:15], v[148:151], v[96:111]
	ds_read_b128 v[8:11], v0 offset:13376
	s_waitcnt lgkmcnt(3)
	v_mfma_f32_32x32x16_bf16 v[80:95], v[248:251], v[128:131], v[80:95]
	ds_read_b128 v[12:15], v0 offset:20032
	s_waitcnt lgkmcnt(3)
	v_mfma_f32_32x32x16_bf16 v[64:79], v[252:255], v[132:135], v[64:79]
	ds_read_b128 v[248:251], v0 offset:13408
	s_waitcnt lgkmcnt(3)
	v_mfma_f32_32x32x16_bf16 v[80:95], v[4:7], v[132:135], v[80:95]
	ds_read_b128 v[252:255], v0 offset:20064
	s_waitcnt lgkmcnt(3)
	v_mfma_f32_32x32x16_bf16 v[64:79], v[8:11], v[136:139], v[64:79]
	ds_read_b128 v[4:7], v0 offset:13440
	s_waitcnt lgkmcnt(3)
	v_mfma_f32_32x32x16_bf16 v[80:95], v[12:15], v[136:139], v[80:95]
	ds_read_b128 v[8:11], v0 offset:20096
	s_waitcnt lgkmcnt(3)
	v_mfma_f32_32x32x16_bf16 v[64:79], v[248:251], v[140:143], v[64:79]
	ds_read_b128 v[12:15], v0 offset:13472
	s_waitcnt lgkmcnt(3)
	v_mfma_f32_32x32x16_bf16 v[80:95], v[252:255], v[140:143], v[80:95]
	ds_read_b128 v[248:251], v0 offset:20128
	s_waitcnt lgkmcnt(3)
	v_mfma_f32_32x32x16_bf16 v[64:79], v[4:7], v[144:147], v[64:79]
	s_waitcnt lgkmcnt(2)
	v_mfma_f32_32x32x16_bf16 v[80:95], v[8:11], v[144:147], v[80:95]
	s_waitcnt lgkmcnt(1)
	v_mfma_f32_32x32x16_bf16 v[64:79], v[12:15], v[148:151], v[64:79]
	s_waitcnt lgkmcnt(0)
	v_mfma_f32_32x32x16_bf16 v[80:95], v[248:251], v[148:151], v[80:95]
	s_nop 0
	v_max_f32_e32 v0, v96, v96
	v_max_f32_e32 v3, v112, v112
	v_max_f32_e32 v0, v3, v0
	s_nop 7
	v_max_f32_e32 v3, v80, v80
	v_max_f32_e32 v4, v64, v64
	v_max_f32_e32 v3, v4, v3
	v_max3_f32 v3, v3, v65, v81
	v_max3_f32 v3, v3, v66, v82
	v_max3_f32 v0, v0, v113, v97
	v_max3_f32 v3, v3, v67, v83
	v_max3_f32 v0, v0, v114, v98
	v_max3_f32 v3, v3, v68, v84
	v_max3_f32 v0, v0, v115, v99
	v_max3_f32 v3, v3, v69, v85
	v_max3_f32 v0, v0, v116, v100
	v_max3_f32 v3, v3, v70, v86
	v_max3_f32 v0, v0, v117, v101
	v_max3_f32 v3, v3, v71, v87
	v_max3_f32 v0, v0, v118, v102
	v_max3_f32 v3, v3, v72, v88
	v_max3_f32 v0, v0, v119, v103
	v_max3_f32 v3, v3, v73, v89
	v_max3_f32 v0, v0, v120, v104
	v_max3_f32 v3, v3, v74, v90
	v_max3_f32 v0, v0, v121, v105
	v_max3_f32 v3, v3, v75, v91
	v_max3_f32 v0, v0, v122, v106
	v_max3_f32 v3, v3, v76, v92
	v_max3_f32 v0, v0, v123, v107
	v_max3_f32 v3, v3, v77, v93
	v_max3_f32 v0, v0, v124, v108
	v_max3_f32 v3, v3, v78, v94
	v_max3_f32 v3, v3, v79, v95
	v_max3_f32 v0, v0, v125, v109
	v_max3_f32 v0, v0, v126, v110
	v_max3_f32 v0, v0, v127, v111
	s_cmp_eq_u32 s31, 1
	v_max_f32_e32 v3, v3, v0
	v_mov_b32_e32 v4, v3
	v_mov_b32_e32 v5, v3
	s_cselect_b64 s[26:27], -1, 0
	s_cmp_lg_u32 s31, 1
	v_permlane32_swap_b32_e32 v4, v5
	v_max_f32_e32 v3, v4, v5
	s_cbranch_scc0 .LBB0_2292
	v_cmp_lt_f32_e32 vcc, s41, v3
	s_mov_b64 s[24:25], 0
	s_mov_b64 s[6:7], 0
	s_cbranch_vccz .LBB0_2285
	v_max_f32_e32 v0, v3, v3
	v_max_f32_e32 v0, 0, v0
	s_mov_b64 s[6:7], -1

; #define LAS __attribute__((address_space(3)))
; __device__ __forceinline__ void a2_exp_pack(f32x16& st0, f32x16& st1, float& lsum, bf16x8 (&pf)[4]) {
;     float ps = 0.f;
; #pragma unroll
;     for (int r = 0; r < 16; ++r) { st0[r] = __builtin_amdgcn_exp2f(st0[r]); st1[r] = __builtin_amdgcn_exp2f(st1[r]); ps += st0[r] + st1[r]; }
;     lsum += ps;
;     u32x4 w;
;     w.x = cvtpk2(st0[0], st0[1]); w.y = cvtpk2(st0[2], st0[3]); w.z = cvtpk2(st0[4], st0[5]); w.w = cvtpk2(st0[6], st0[7]); pf[0] = __builtin_bit_cast(bf16x8, w);
;     w.x = cvtpk2(st0[8], st0[9]); w.y = cvtpk2(st0[10], st0[11]); w.z = cvtpk2(st0[12], st0[13]); w.w = cvtpk2(st0[14], st0[15]); pf[1] = __builtin_bit_cast(bf16x8, w);
;     w.x = cvtpk2(st1[0], st1[1]); w.y = cvtpk2(st1[2], st1[3]); w.z = cvtpk2(st1[4], st1[5]); w.w = cvtpk2(st1[6], st1[7]); pf[2] = __builtin_bit_cast(bf16x8, w);
;     w.x = cvtpk2(st1[8], st1[9]); w.y = cvtpk2(st1[10], st1[11]); w.z = cvtpk2(st1[12], st1[13]); w.w = cvtpk2(st1[14], st1[15]); pf[3] = __builtin_bit_cast(bf16x8, w);
; }
; __device__ __forceinline__ void a2_pv(const LAS unsigned char* vb, const bf16x8 (&pf)[4], f32x16& ot0, f32x16& ot1) {
; #pragma unroll
;     for (int s = 0; s < 4; ++s) {
;         const s16x4 a00 = __builtin_bit_cast(s16x4, __builtin_amdgcn_ds_read_tr16_b64_v4i16((LAS s16x4*)(vb + (16 * s) * 64)));
;         const s16x4 a01 = __builtin_bit_cast(s16x4, __builtin_amdgcn_ds_read_tr16_b64_v4i16((LAS s16x4*)(vb + (16 * s + 8) * 64)));
;         const s16x4 a10 = __builtin_bit_cast(s16x4, __builtin_amdgcn_ds_read_tr16_b64_v4i16((LAS s16x4*)(vb + 8192 + (16 * s) * 64)));
;         const s16x4 a11 = __builtin_bit_cast(s16x4, __builtin_amdgcn_ds_read_tr16_b64_v4i16((LAS s16x4*)(vb + 8192 + (16 * s + 8) * 64)));
;         const bf16x8 va0 = (bf16x8){a00[0], a00[1], a00[2], a00[3], a01[0], a01[1], a01[2], a01[3]};
;         const bf16x8 va1 = (bf16x8){a10[0], a10[1], a10[2], a10[3], a11[0], a11[1], a11[2], a11[3]};
; __device__ __forceinline__ void attn2_unit(bf16_t* Z, const bf16_t* Hb, const float* rc, const float* rs, LAS unsigned char* lds, int b, int h, int qblk) {
;     ...
;             a2_exp_pack(sa0, sa1, lsum, pa);
;             a2_pv(vb, pa, ot0, ot1);
;             a2_exp_pack(sb0, sb1, lsum, pb);
;             a2_pv(vb + 64 * 64, pb, ot0, ot1);
.LBB0_2289:
	s_setprio 0
	v_add_u32_e32 v0, v2, v218
	v_exp_f32_e32 v195, v112
	v_exp_f32_e32 v7, v96
	v_exp_f32_e32 v113, v113
	v_exp_f32_e32 v9, v97
	v_exp_f32_e32 v199, v114
	v_exp_f32_e32 v3, v98
	v_exp_f32_e32 v115, v115
	v_exp_f32_e32 v5, v99
	v_exp_f32_e32 v201, v116
	v_exp_f32_e32 v15, v117
	v_exp_f32_e32 v13, v118
	v_exp_f32_e32 v11, v119
	s_waitcnt vmcnt(0)
	ds_read_b64_tr_b16 v[96:97], v0 offset:26624
	ds_read_b64_tr_b16 v[98:99], v0 offset:27136
	ds_read_b64_tr_b16 v[212:213], v0 offset:34816
	ds_read_b64_tr_b16 v[214:215], v0 offset:35328
	ds_read_b64_tr_b16 v[220:221], v0 offset:27648
	ds_read_b64_tr_b16 v[222:223], v0 offset:28160
	v_cvt_pk_bf16_f32 v208, v195, v113
	v_cvt_pk_bf16_f32 v209, v199, v115
	v_cvt_pk_bf16_f32 v210, v201, v15
	v_cvt_pk_bf16_f32 v211, v13, v11
	v_exp_f32_e32 v207, v120
	v_exp_f32_e32 v205, v121
	s_waitcnt lgkmcnt(4)
	v_mfma_f32_32x32x16_bf16 v[16:31], v[96:99], v[208:211], v[16:31]
	v_exp_f32_e32 v203, v122
	v_exp_f32_e32 v121, v123
	v_exp_f32_e32 v117, v124
	ds_read_b64_tr_b16 v[224:225], v0 offset:35840
	ds_read_b64_tr_b16 v[226:227], v0 offset:36352
	v_exp_f32_e32 v119, v125
	v_exp_f32_e32 v99, v126
	v_exp_f32_e32 v97, v127
	s_waitcnt lgkmcnt(4)
	v_mfma_f32_32x32x16_bf16 v[32:47], v[212:215], v[208:211], v[32:47]
	v_cvt_pk_bf16_f32 v228, v207, v205
	v_cvt_pk_bf16_f32 v229, v203, v121
	v_cvt_pk_bf16_f32 v230, v117, v119
	v_cvt_pk_bf16_f32 v231, v99, v97
	v_exp_f32_e32 v125, v100
	v_exp_f32_e32 v211, v101
	v_exp_f32_e32 v209, v102
	s_waitcnt lgkmcnt(2)
	v_mfma_f32_32x32x16_bf16 v[16:31], v[220:223], v[228:231], v[16:31]
	v_exp_f32_e32 v215, v103
	ds_read_b64_tr_b16 v[220:221], v0 offset:28672
	ds_read_b64_tr_b16 v[222:223], v0 offset:29184
	v_cvt_pk_bf16_f32 v100, v7, v9
	v_cvt_pk_bf16_f32 v101, v3, v5
	v_cvt_pk_bf16_f32 v102, v125, v211
	v_cvt_pk_bf16_f32 v103, v209, v215
	v_exp_f32_e32 v123, v104
	s_waitcnt lgkmcnt(2)
	v_mfma_f32_32x32x16_bf16 v[32:47], v[224:227], v[228:231], v[32:47]
	ds_read_b64_tr_b16 v[224:225], v0 offset:36864
	ds_read_b64_tr_b16 v[226:227], v0 offset:37376
	ds_read_b64_tr_b16 v[228:229], v0 offset:29696
	ds_read_b64_tr_b16 v[230:231], v0 offset:30208
	v_exp_f32_e32 v127, v105
	v_exp_f32_e32 v105, v106
	v_exp_f32_e32 v213, v107
	v_exp_f32_e32 v107, v108
	v_exp_f32_e32 v109, v109
	v_exp_f32_e32 v194, v64
	s_waitcnt lgkmcnt(4)
	v_mfma_f32_32x32x16_bf16 v[16:31], v[220:223], v[100:103], v[16:31]
	ds_read_b64_tr_b16 v[220:221], v0 offset:37888
	ds_read_b64_tr_b16 v[222:223], v0 offset:38400
	v_exp_f32_e32 v6, v80
	v_exp_f32_e32 v112, v65
	v_exp_f32_e32 v8, v81
	v_exp_f32_e32 v198, v66
	v_exp_f32_e32 v2, v82
	v_exp_f32_e32 v114, v67
	s_waitcnt lgkmcnt(4)
	v_mfma_f32_32x32x16_bf16 v[32:47], v[224:227], v[100:103], v[32:47]
	v_exp_f32_e32 v103, v110
	v_exp_f32_e32 v101, v111
	v_exp_f32_e32 v4, v83
	v_cvt_pk_bf16_f32 v224, v123, v127
	v_cvt_pk_bf16_f32 v225, v105, v213
	v_cvt_pk_bf16_f32 v226, v107, v109
	v_cvt_pk_bf16_f32 v227, v103, v101
	v_pk_add_f32 v[64:65], v[6:7], v[194:195]
	v_pk_add_f32 v[66:67], v[8:9], v[112:113]
	s_waitcnt lgkmcnt(2)
	v_mfma_f32_32x32x16_bf16 v[16:31], v[228:231], v[224:227], v[16:31]
	v_add_f32_e64 v64, v64, 0
	v_add_f32_e64 v65, v65, 0
	v_exp_f32_e32 v200, v68
	v_pk_add_f32 v[64:65], v[66:67], v[64:65]
	v_pk_add_f32 v[66:67], v[2:3], v[198:199]
	v_exp_f32_e32 v14, v69
	v_pk_add_f32 v[64:65], v[66:67], v[64:65]
	v_pk_add_f32 v[66:67], v[4:5], v[114:115]
	s_waitcnt lgkmcnt(0)
	v_mfma_f32_32x32x16_bf16 v[32:47], v[220:223], v[224:227], v[32:47]
	v_add_f32_e64 v110, v66, v64
	v_add_f32_e64 v111, v67, v65
	v_exp_f32_e32 v12, v70
	v_exp_f32_e32 v10, v71
	ds_read_b64_tr_b16 v[64:65], v0 offset:30720
	ds_read_b64_tr_b16 v[66:67], v0 offset:31232
	v_exp_f32_e32 v124, v84
	v_exp_f32_e32 v206, v72
	v_exp_f32_e32 v204, v73
	v_exp_f32_e32 v202, v74
	v_exp_f32_e32 v120, v75
	ds_read_b64_tr_b16 v[72:73], v0 offset:38912
	ds_read_b64_tr_b16 v[74:75], v0 offset:39424
	ds_read_b64_tr_b16 v[80:81], v0 offset:31744
	ds_read_b64_tr_b16 v[82:83], v0 offset:32256
	v_exp_f32_e32 v210, v85
	v_cvt_pk_bf16_f32 v68, v194, v112
	v_cvt_pk_bf16_f32 v69, v198, v114
	v_cvt_pk_bf16_f32 v70, v200, v14
	v_cvt_pk_bf16_f32 v71, v12, v10
	v_pk_add_f32 v[216:217], v[124:125], v[200:201]
	v_exp_f32_e32 v208, v86
	s_waitcnt lgkmcnt(4)
; __device__ __forceinline__ void attn2_unit(bf16_t* Z, const bf16_t* Hb, const float* rc, const float* rs, LAS unsigned char* lds, int b, int h, int qblk) {
;     ...
;             a2_exp_pack(sa0, sa1, lsum, pa);
;             a2_pv(vb, pa, ot0, ot1);
;             a2_exp_pack(sb0, sb1, lsum, pb);
;             a2_pv(vb + 64 * 64, pb, ot0, ot1);
;         } else if (2 * kp <= cw) {
;             f32x16 sa0, sa1; bf16x8 pa[4];
;             a2_qk(kb, qf, cneg, sa0, sa1);
;             const float mt = a2_max(sa0, sa1);
;             if (kp == 0 || __builtin_amdgcn_ballot_w64(mt > 8.f) != 0ull) {
;                 const float delta = (kp == 0) ? mt : fmaxf(mt, 0.f), alpha = (kp == 0) ? 0.f : __builtin_amdgcn_exp2f(-delta);
;                 mrun += delta; lsum *= alpha;
; #pragma unroll
;                 for (int r = 0; r < 16; ++r) { ot0[r] *= alpha; ot1[r] *= alpha; sa0[r] -= delta; sa1[r] -= delta; cneg[r] = -mrun; }
;             }
;             a2_exp_pack(sa0, sa1, lsum, pa);
;             a2_pv(vb, pa, ot0, ot1);
;         }
;         __syncthreads();
;     }
	v_mfma_f32_32x32x16_bf16 v[16:31], v[64:67], v[68:71], v[16:31]
	v_add_f32_e64 v64, v216, v110
	v_add_f32_e64 v65, v217, v111
	v_add_f32_e64 v14, v210, v14
	v_add_f32_e64 v15, v211, v15
	v_exp_f32_e32 v214, v87
	v_exp_f32_e32 v116, v76
	v_exp_f32_e32 v118, v77
	v_exp_f32_e32 v98, v78
	v_exp_f32_e32 v96, v79
	s_waitcnt lgkmcnt(2)
	v_mfma_f32_32x32x16_bf16 v[32:47], v[72:75], v[68:71], v[32:47]
	v_add_f32_e64 v14, v14, v64
	v_add_f32_e64 v15, v15, v65
	ds_read_b64_tr_b16 v[64:65], v0 offset:39936
	ds_read_b64_tr_b16 v[66:67], v0 offset:40448
	v_exp_f32_e32 v122, v88
	v_pk_add_f32 v[12:13], v[208:209], v[12:13]
	v_pk_add_f32 v[68:69], v[214:215], v[10:11]
	v_pk_add_f32 v[14:15], v[12:13], v[14:15]
	v_cvt_pk_bf16_f32 v10, v206, v204
	v_cvt_pk_bf16_f32 v11, v202, v120
	v_cvt_pk_bf16_f32 v12, v116, v118
	v_cvt_pk_bf16_f32 v13, v98, v96
	v_pk_add_f32 v[14:15], v[68:69], v[14:15]
	v_pk_add_f32 v[68:69], v[122:123], v[206:207]
	s_waitcnt lgkmcnt(2)
	v_mfma_f32_32x32x16_bf16 v[16:31], v[80:83], v[10:13], v[16:31]
	v_add_f32_e64 v14, v68, v14
	v_add_f32_e64 v15, v69, v15
	ds_read_b64_tr_b16 v[68:69], v0 offset:32768
	ds_read_b64_tr_b16 v[70:71], v0 offset:33280
	v_exp_f32_e32 v126, v89
	v_exp_f32_e32 v104, v90
	v_cvt_pk_bf16_f32 v7, v2, v4
	v_exp_f32_e32 v212, v91
	v_cvt_pk_bf16_f32 v6, v6, v8
	s_waitcnt lgkmcnt(2)
	v_mfma_f32_32x32x16_bf16 v[32:47], v[64:67], v[10:13], v[32:47]
	ds_read_b64_tr_b16 v[2:3], v0 offset:40960
	ds_read_b64_tr_b16 v[4:5], v0 offset:41472
	ds_read_b64_tr_b16 v[10:11], v0 offset:33792
	ds_read_b64_tr_b16 v[12:13], v0 offset:34304
	v_cvt_pk_bf16_f32 v8, v124, v210
	v_cvt_pk_bf16_f32 v9, v208, v214
	v_pk_add_f32 v[72:73], v[126:127], v[204:205]
	v_pk_add_f32 v[64:65], v[104:105], v[202:203]
	v_pk_add_f32 v[14:15], v[72:73], v[14:15]
	v_exp_f32_e32 v106, v92
	s_waitcnt lgkmcnt(4)
	v_mfma_f32_32x32x16_bf16 v[16:31], v[68:71], v[6:9], v[16:31]
	v_add_f32_e64 v14, v64, v14
	v_add_f32_e64 v15, v65, v15
	v_add_f32_e64 v64, v212, v120
	v_add_f32_e64 v65, v213, v121
	v_exp_f32_e32 v108, v93
	v_exp_f32_e32 v102, v94
	v_exp_f32_e32 v100, v95
	v_pk_add_f32 v[14:15], v[64:65], v[14:15]
	ds_read_b64_tr_b16 v[64:65], v0 offset:41984
	ds_read_b64_tr_b16 v[66:67], v0 offset:42496
	s_waitcnt lgkmcnt(4)
	v_mfma_f32_32x32x16_bf16 v[32:47], v[2:5], v[6:9], v[32:47]
	v_add_f32_e64 v2, v106, v116
	v_add_f32_e64 v3, v107, v117
	v_cvt_pk_bf16_f32 v4, v106, v108
	v_add_f32_e64 v6, v2, v14
	v_add_f32_e64 v7, v3, v15
	v_cvt_pk_bf16_f32 v2, v122, v126
	v_cvt_pk_bf16_f32 v3, v104, v212
	v_cvt_pk_bf16_f32 v5, v102, v100
	v_pk_add_f32 v[8:9], v[108:109], v[118:119]
	v_mov_b32_e32 v14, v55
	s_waitcnt lgkmcnt(2)
	v_mfma_f32_32x32x16_bf16 v[16:31], v[10:13], v[2:5], v[16:31]
	v_add_f32_e64 v6, v8, v6
	v_add_f32_e64 v7, v9, v7
	v_add_f32_e64 v8, v102, v98
	v_add_f32_e64 v9, v103, v99
	v_mov_b32_e32 v10, v59
	v_pk_add_f32 v[6:7], v[8:9], v[6:7]
	v_pk_add_f32 v[8:9], v[100:101], v[96:97]
	v_mov_b32_e32 v11, v58
	v_pk_add_f32 v[6:7], v[8:9], v[6:7]
	s_waitcnt lgkmcnt(0)
	v_mfma_f32_32x32x16_bf16 v[32:47], v[64:67], v[2:5], v[32:47]
	v_add_f32_e32 v0, v169, v7
	v_add_f32_e32 v0, v6, v0
	s_add_i32 s31, s31, 1
	s_add_i32 s42, s42, 2
	s_add_i32 s6, s38, s31
	v_lshl_add_u64 v[174:175], v[174:175], 0, v[170:171]
	v_lshl_add_u64 v[176:177], v[176:177], 0, s[18:19]
	v_lshl_add_u64 v[178:179], v[178:179], 0, s[18:19]
	v_lshl_add_u64 v[182:183], v[182:183], 0, v[180:181]
	v_lshl_add_u64 v[186:187], v[186:187], 0, v[184:185]
	s_cmp_lg_u32 s6, 1
	v_lshl_add_u64 v[190:191], v[190:191], 0, v[188:189]
	s_waitcnt vmcnt(0) lgkmcnt(0)
	s_barrier
	s_cbranch_scc0 .Lattn_exit_3
	v_mov_b32_e32 v169, v0
	s_bitcmp1_b32 s31, 0
	s_cselect_b32 s6, 0, 0xa800
	s_cmp_ge_u32 s31, s36
	s_cbranch_scc0 .LBB0_2267
	s_branch .LBB0_2270
